# lever 4: one static s_setprio 1 for blocks >= grid/2 (the co-resident workgroup of each CU), per-segment s_setprio toggles around MFMA blocks removed
# speedup vs baseline: 1.0094x; 1.0094x over previous
; #define LAS __attribute__((address_space(3)))
; DI unsigned xb_add(unsigned* p, unsigned v) { return __hip_atomic_fetch_add(p, v, __ATOMIC_RELAXED, __HIP_MEMORY_SCOPE_AGENT); }
; DI unsigned xb_xcc_id() { return (unsigned)__builtin_amdgcn_s_getreg((3 << 11) | 20) & 0xFu; }
; DI XcdBarrier xcd_barrier_post(unsigned* bar, volatile LAS unsigned* st) {
;   XcdBarrier b; b.bar = bar; b.x = xb_xcc_id(); b.st = st;
;   if (threadIdx.x == 0) (void)xb_add(&bar[XB_XCNT(b.x)], 1u);
;   return b;
; __global__ void __launch_bounds__(256, 2) fwd_megakernel(Params p) {
;   cg::grid_group grid = cg::this_grid();
;   __shared__ __attribute__((aligned(16))) unsigned char smem[SMEM_BYTES];
;   unsigned char* ws = p.ws;
;   __shared__ __attribute__((aligned(16))) unsigned xb_words[4];
;   if (threadIdx.x < 4) xb_words[threadIdx.x] = 0u;
;   __syncthreads();
;   XcdBarrier gbar = xcd_barrier_post((unsigned*)(ws + OFF_BAR), (volatile LAS unsigned*)&xb_words);
_Z14fwd_megakernel6Params:
	v_and_b32_e32 v160, 0x3ff, v0
	v_writelane_b32 v255, s2, 0
	v_cmp_gt_u32_e32 vcc, 4, v160
	s_nop 0
	v_writelane_b32 v255, s3, 1
	s_mov_b64 s[2:3], s[0:1]
	s_load_dword s0, s[0:1], 0x210
	s_nop 0
	s_load_dwordx2 s[26:27], s[2:3], 0x208
	s_load_dwordx2 s[22:23], s[2:3], 0x80
	s_add_u32 s8, s2, 0x208
	s_addc_u32 s9, s3, 0
	s_waitcnt lgkmcnt(0)
	v_readlane_b32 s98, v255, 0
	s_lshr_b32 s99, s26, 1
	s_cmp_ge_u32 s98, s99
	s_cbranch_scc0 .Lmy_sprio
	s_setprio 1
.Lmy_sprio:
	v_writelane_b32 v255, s0, 2
	s_and_saveexec_b64 s[4:5], vcc
	v_mov_b32_e32 v1, 0x10800
	v_lshl_add_u32 v1, v160, 2, v1
	v_mov_b32_e32 v2, 0
	ds_write_b32 v1, v2
	s_or_b64 exec, exec, s[4:5]
	s_add_u32 s0, s22, 0x1c100000
	s_addc_u32 s1, s23, 0
	v_writelane_b32 v255, s0, 3
	s_waitcnt lgkmcnt(0)
	s_barrier
	v_writelane_b32 v255, s1, 4
	s_getreg_b32 s0, hwreg(HW_REG_XCC_ID, 0, 4)
	s_and_b32 s24, s0, 15
	v_readlane_b32 s0, v255, 0
	v_readlane_b32 s1, v255, 1
	s_mov_b32 s1, 0
	v_writelane_b32 v255, s0, 0
	v_mov_b64_e32 v[18:19], s[22:23]
	s_nop 0
	v_writelane_b32 v255, s1, 1
	v_cmp_eq_u32_e64 s[0:1], 0, v160
	s_mov_b64 s[6:7], exec
	s_nop 0
	v_writelane_b32 v255, s0, 5
	s_nop 1
	v_writelane_b32 v255, s1, 6
	s_and_b64 s[0:1], s[6:7], s[0:1]
	s_mov_b64 exec, s[0:1]
	s_cbranch_execz .LBB0_6
	s_mov_b64 s[12:13], exec
	v_mbcnt_lo_u32_b32 v1, s12, 0
	v_mbcnt_hi_u32_b32 v1, s13, v1
	v_cmp_eq_u32_e32 vcc, 0, v1
	v_mov_b64_e32 v[18:19], s[22:23]
	s_and_saveexec_b64 s[10:11], vcc
	s_cbranch_execz .LBB0_5
	s_lshl_b32 s0, s24, 8
	s_bcnt1_i32_b64 s1, s[12:13]
	v_mov_b32_e32 v1, s0
	v_mov_b32_e32 v2, s1
	v_readlane_b32 s0, v255, 3
	v_readlane_b32 s1, v255, 4
	v_mov_b64_e32 v[18:19], s[22:23]
	s_nop 3
	global_atomic_add v1, v2, s[0:1] offset:1024

; #define MFMA(a, b, c) __builtin_amdgcn_mfma_f32_32x32x16_bf16((a), (b), (c), 0, 0, 0)
; DI void gt_compute(const bf16* asr, const bf16* bsr, f32x16& acc0, f32x16& acc1, f32x16& acc2, f32x16& acc3) {
;   bf16x8 a[4], b0[4], b1[4], b2[4], b3[4];
; #pragma unroll
;   for (int kk = 0; kk < 4; ++kk) {
;     a[kk] = *(const bf16x8*)(asr + kk * 16);
;     b0[kk] = *(const bf16x8*)(bsr + kk * 16);
;     b1[kk] = *(const bf16x8*)(bsr + 32 * LDT + kk * 16);
;     b2[kk] = *(const bf16x8*)(bsr + 64 * LDT + kk * 16);
;     b3[kk] = *(const bf16x8*)(bsr + 96 * LDT + kk * 16);
;   }
;   __builtin_amdgcn_sched_barrier(0);
;   __builtin_amdgcn_s_setprio(2);
; #pragma unroll
;   for (int kk = 0; kk < 4; ++kk) {
;     acc0 = MFMA(a[kk], b0[kk], acc0); acc1 = MFMA(a[kk], b1[kk], acc1); acc2 = MFMA(a[kk], b2[kk], acc2); acc3 = MFMA(a[kk], b3[kk], acc3);
;   }
;   __builtin_amdgcn_s_setprio(0);
;   __builtin_amdgcn_sched_barrier(0);
; }
.LBB0_228:
	ds_read_b128 v[146:149], v142
	ds_read_b128 v[150:153], v142 offset:32
	ds_read_b128 v[154:157], v130 offset:18432
	ds_read_b128 v[162:165], v130 offset:18464
	ds_read_b128 v[166:169], v130 offset:23040
	ds_read_b128 v[170:173], v130 offset:23072
	ds_read_b128 v[174:177], v130 offset:27648
	ds_read_b128 v[178:181], v130 offset:27680
	ds_read_b128 v[182:185], v130 offset:32256
	ds_read_b128 v[186:189], v130 offset:32288
	ds_read_b128 v[190:193], v142 offset:64
	ds_read_b128 v[194:197], v142 offset:96
	ds_read_b128 v[198:201], v130 offset:18496
	ds_read_b128 v[202:205], v130 offset:18528
	ds_read_b128 v[206:209], v130 offset:23104
	ds_read_b128 v[210:213], v130 offset:23136
	ds_read_b128 v[214:217], v130 offset:27712
	ds_read_b128 v[218:221], v130 offset:27744
	ds_read_b128 v[222:225], v130 offset:32320
	ds_read_b128 v[226:229], v130 offset:32352
	s_waitcnt lgkmcnt(14)
	v_mfma_f32_32x32x16_bf16 v[48:63], v[146:149], v[154:157], v[48:63]
	v_mfma_f32_32x32x16_bf16 v[32:47], v[146:149], v[166:169], v[32:47]
	s_waitcnt lgkmcnt(13)
	v_mfma_f32_32x32x16_bf16 v[16:31], v[146:149], v[174:177], v[16:31]
	s_waitcnt lgkmcnt(11)
	v_mfma_f32_32x32x16_bf16 v[0:15], v[146:149], v[182:185], v[0:15]
	v_mfma_f32_32x32x16_bf16 v[48:63], v[150:153], v[162:165], v[48:63]
	v_mfma_f32_32x32x16_bf16 v[32:47], v[150:153], v[170:173], v[32:47]
	v_mfma_f32_32x32x16_bf16 v[16:31], v[150:153], v[178:181], v[16:31]
	s_waitcnt lgkmcnt(10)
	v_mfma_f32_32x32x16_bf16 v[0:15], v[150:153], v[186:189], v[0:15]
	s_waitcnt lgkmcnt(7)
	v_mfma_f32_32x32x16_bf16 v[48:63], v[190:193], v[198:201], v[48:63]
	s_waitcnt lgkmcnt(5)
	v_mfma_f32_32x32x16_bf16 v[32:47], v[190:193], v[206:209], v[32:47]
	s_waitcnt lgkmcnt(3)
	v_mfma_f32_32x32x16_bf16 v[16:31], v[190:193], v[214:217], v[16:31]
	s_waitcnt lgkmcnt(1)
	v_mfma_f32_32x32x16_bf16 v[0:15], v[190:193], v[222:225], v[0:15]
	v_mfma_f32_32x32x16_bf16 v[48:63], v[194:197], v[202:205], v[48:63]
	v_mfma_f32_32x32x16_bf16 v[32:47], v[194:197], v[210:213], v[32:47]
	v_mfma_f32_32x32x16_bf16 v[16:31], v[194:197], v[218:221], v[16:31]
	s_waitcnt lgkmcnt(0)
	v_mfma_f32_32x32x16_bf16 v[0:15], v[194:197], v[226:229], v[0:15]
	s_add_i32 s0, s28, 0xffffff80
	s_cmpk_lt_u32 s0, 0x380
	s_mov_b64 s[20:21], s[28:29]
	s_cbranch_scc0 .LBB0_233

; #define MFMA(a, b, c) __builtin_amdgcn_mfma_f32_32x32x16_bf16((a), (b), (c), 0, 0, 0)
; DI void gt_compute(const bf16* asr, const bf16* bsr, f32x16& acc0, f32x16& acc1, f32x16& acc2, f32x16& acc3) {
;   bf16x8 a[4], b0[4], b1[4], b2[4], b3[4];
; #pragma unroll
;   for (int kk = 0; kk < 4; ++kk) {
;     a[kk] = *(const bf16x8*)(asr + kk * 16);
;     b0[kk] = *(const bf16x8*)(bsr + kk * 16);
;     b1[kk] = *(const bf16x8*)(bsr + 32 * LDT + kk * 16);
;     b2[kk] = *(const bf16x8*)(bsr + 64 * LDT + kk * 16);
;     b3[kk] = *(const bf16x8*)(bsr + 96 * LDT + kk * 16);
;   }
;   __builtin_amdgcn_sched_barrier(0);
;   __builtin_amdgcn_s_setprio(2);
; #pragma unroll
;   for (int kk = 0; kk < 4; ++kk) {
;     acc0 = MFMA(a[kk], b0[kk], acc0); acc1 = MFMA(a[kk], b1[kk], acc1); acc2 = MFMA(a[kk], b2[kk], acc2); acc3 = MFMA(a[kk], b3[kk], acc3);
;   }
;   __builtin_amdgcn_s_setprio(0);
;   __builtin_amdgcn_sched_barrier(0);
; }
; DI void gemm_mainloop(const bf16* __restrict__ A, int lda, const bf16* __restrict__ Bt, int ldb, int K, int m0, int n0,
;                       bf16* As, bf16* Bs, f32x16& acc0, f32x16& acc1, f32x16& acc2, f32x16& acc3) {
;     ...
;   for (int k0 = 0; k0 < K; k0 += 128) {
;     __syncthreads();
;     gt_store(t0, asw, bsw);
;     __syncthreads();
;     if (k0 + 128 < K) gt_load(t0, ap, bp, lda, ldb, KW(k0 + 128));
;     gt_compute(asr, bsr, acc0, acc1, acc2, acc3);
;     __syncthreads();
;     gt_store(t1, asw, bsw);
;     __syncthreads();
;     if (k0 + 192 < K) gt_load(t1, ap, bp, lda, ldb, KW(k0 + 192));
;     gt_compute(asr, bsr, acc0, acc1, acc2, acc3);
;   }
.LBB0_231:
	ds_read_b128 v[146:149], v142
	ds_read_b128 v[150:153], v142 offset:32
	ds_read_b128 v[154:157], v130 offset:18432
	ds_read_b128 v[162:165], v130 offset:18464
	ds_read_b128 v[166:169], v130 offset:23040
	ds_read_b128 v[170:173], v130 offset:23072
	ds_read_b128 v[174:177], v130 offset:27648
	ds_read_b128 v[178:181], v130 offset:27680
	ds_read_b128 v[182:185], v130 offset:32256
	ds_read_b128 v[186:189], v130 offset:32288
	ds_read_b128 v[190:193], v142 offset:64
	ds_read_b128 v[194:197], v142 offset:96
	ds_read_b128 v[198:201], v130 offset:18496
	ds_read_b128 v[202:205], v130 offset:18528
	ds_read_b128 v[206:209], v130 offset:23104
	ds_read_b128 v[210:213], v130 offset:23136
	ds_read_b128 v[214:217], v130 offset:27712
	ds_read_b128 v[218:221], v130 offset:27744
	ds_read_b128 v[222:225], v130 offset:32320
	ds_read_b128 v[226:229], v130 offset:32352
	s_waitcnt lgkmcnt(14)
	v_mfma_f32_32x32x16_bf16 v[48:63], v[146:149], v[154:157], v[48:63]
	v_mfma_f32_32x32x16_bf16 v[32:47], v[146:149], v[166:169], v[32:47]
	s_waitcnt lgkmcnt(13)
	v_mfma_f32_32x32x16_bf16 v[16:31], v[146:149], v[174:177], v[16:31]
	s_waitcnt lgkmcnt(11)
	v_mfma_f32_32x32x16_bf16 v[0:15], v[146:149], v[182:185], v[0:15]
	v_mfma_f32_32x32x16_bf16 v[48:63], v[150:153], v[162:165], v[48:63]
	v_mfma_f32_32x32x16_bf16 v[32:47], v[150:153], v[170:173], v[32:47]
	v_mfma_f32_32x32x16_bf16 v[16:31], v[150:153], v[178:181], v[16:31]
	s_waitcnt lgkmcnt(10)
	v_mfma_f32_32x32x16_bf16 v[0:15], v[150:153], v[186:189], v[0:15]
	s_waitcnt lgkmcnt(7)
	v_mfma_f32_32x32x16_bf16 v[48:63], v[190:193], v[198:201], v[48:63]
	s_waitcnt lgkmcnt(5)
	v_mfma_f32_32x32x16_bf16 v[32:47], v[190:193], v[206:209], v[32:47]
	s_waitcnt lgkmcnt(3)
	v_mfma_f32_32x32x16_bf16 v[16:31], v[190:193], v[214:217], v[16:31]
	s_waitcnt lgkmcnt(1)
	v_mfma_f32_32x32x16_bf16 v[0:15], v[190:193], v[222:225], v[0:15]
	v_mfma_f32_32x32x16_bf16 v[48:63], v[194:197], v[202:205], v[48:63]
	v_mfma_f32_32x32x16_bf16 v[32:47], v[194:197], v[210:213], v[32:47]
	v_mfma_f32_32x32x16_bf16 v[16:31], v[194:197], v[218:221], v[16:31]
	s_waitcnt lgkmcnt(0)
	v_mfma_f32_32x32x16_bf16 v[0:15], v[194:197], v[226:229], v[0:15]
	s_cmpk_gt_u32 s20, 0x33f
	s_barrier
	s_waitcnt vmcnt(5)
	ds_write_b128 v140, v[104:107]
	ds_write_b128 v140, v[88:91] offset:4608
	ds_write_b128 v140, v[92:95] offset:9216
	s_waitcnt vmcnt(3)
	ds_write_b128 v140, v[112:115] offset:13824
	ds_write_b128 v140, v[108:111] offset:18432
	s_waitcnt vmcnt(2)
	ds_write_b128 v140, v[116:119] offset:23040
	s_waitcnt vmcnt(1)
	ds_write_b128 v140, v[120:123] offset:27648
	s_waitcnt vmcnt(0)
	ds_write_b128 v140, v[124:127] offset:32256
	s_waitcnt lgkmcnt(0)
	s_barrier
	s_cbranch_scc1 .LBB0_228
	s_cmp_lt_i32 s20, s17
	s_cselect_b32 s1, 0, -1
	s_cselect_b32 s0, 0, 0xfffffc00
	s_add_u32 s20, s18, s20
	s_addc_u32 s21, s19, s21
	s_add_u32 s0, s20, s0
	s_addc_u32 s1, s21, s1
	s_lshl_b64 s[0:1], s[0:1], 1
	v_lshl_add_u64 v[104:105], v[136:137], 0, s[0:1]
	v_add_co_u32_e32 v106, vcc, s48, v104
	v_lshl_add_u64 v[120:121], v[138:139], 0, s[0:1]
	s_nop 0
	v_addc_co_u32_e32 v107, vcc, 0, v105, vcc
	v_add_co_u32_e32 v108, vcc, 0x20000, v104
	s_nop 1
	v_addc_co_u32_e32 v109, vcc, 0, v105, vcc
	v_add_co_u32_e32 v112, vcc, 0x30000, v104
	global_load_dwordx4 v[88:91], v[106:107], off offset:384
	global_load_dwordx4 v[92:95], v[108:109], off offset:384
	v_addc_co_u32_e32 v113, vcc, 0, v105, vcc
	v_add_co_u32_e32 v116, vcc, 0x10000, v120
	global_load_dwordx4 v[104:107], v[104:105], off offset:384
	s_nop 0
	global_load_dwordx4 v[108:111], v[120:121], off offset:384
	v_addc_co_u32_e32 v117, vcc, 0, v121, vcc
	v_add_co_u32_e32 v122, vcc, 0x20000, v120
	global_load_dwordx4 v[112:115], v[112:113], off offset:384
	s_nop 0
	global_load_dwordx4 v[116:119], v[116:117], off offset:384
	v_addc_co_u32_e32 v123, vcc, 0, v121, vcc
	v_add_co_u32_e32 v124, vcc, 0x30000, v120
	s_nop 1
	v_addc_co_u32_e32 v125, vcc, 0, v121, vcc
	global_load_dwordx4 v[120:123], v[122:123], off offset:384
	s_nop 0
	global_load_dwordx4 v[124:127], v[124:125], off offset:384
	s_branch .LBB0_228

; #define MFMA(a, b, c) __builtin_amdgcn_mfma_f32_32x32x16_bf16((a), (b), (c), 0, 0, 0)
; DI void gt_compute(const bf16* asr, const bf16* bsr, f32x16& acc0, f32x16& acc1, f32x16& acc2, f32x16& acc3) {
;   bf16x8 a[4], b0[4], b1[4], b2[4], b3[4];
; #pragma unroll
;   for (int kk = 0; kk < 4; ++kk) {
;     a[kk] = *(const bf16x8*)(asr + kk * 16);
;     b0[kk] = *(const bf16x8*)(bsr + kk * 16);
;     b1[kk] = *(const bf16x8*)(bsr + 32 * LDT + kk * 16);
;     b2[kk] = *(const bf16x8*)(bsr + 64 * LDT + kk * 16);
;     b3[kk] = *(const bf16x8*)(bsr + 96 * LDT + kk * 16);
;   }
;   __builtin_amdgcn_sched_barrier(0);
;   __builtin_amdgcn_s_setprio(2);
; #pragma unroll
;   for (int kk = 0; kk < 4; ++kk) {
;     acc0 = MFMA(a[kk], b0[kk], acc0); acc1 = MFMA(a[kk], b1[kk], acc1); acc2 = MFMA(a[kk], b2[kk], acc2); acc3 = MFMA(a[kk], b3[kk], acc3);
;   }
;   __builtin_amdgcn_s_setprio(0);
;   __builtin_amdgcn_sched_barrier(0);
; }
; DI void gemm_mainloop(const bf16* __restrict__ A, int lda, const bf16* __restrict__ Bt, int ldb, int K, int m0, int n0,
;                       bf16* As, bf16* Bs, f32x16& acc0, f32x16& acc1, f32x16& acc2, f32x16& acc3) {
;   const int tid = opaque_tid(), lane = tid & 63, w = tid >> 6, r = lane & 31, g = lane >> 5;
;   const int lrow = tid >> 3, lcc = (tid & 7) * 8;
;   const bf16* ap = A + (size_t)(m0 + lrow) * lda + lcc;
;   const bf16* bp = Bt + (size_t)(n0 + lrow) * ldb + lcc;
;   GTile t0, t1;
;   asm volatile("" ::: "memory");
;   const int nkt = K >> 6;
;   int kb = ((((m0 >> 7) * 5 + (n0 >> 7) * 3) >> 1) % nkt) << 6;
;     ...
;   gt_load(t0, ap, bp, lda, ldb, KW(0));
;   gt_load(t1, ap, bp, lda, ldb, KW(64));
; #pragma unroll
;   for (int i = 0; i < 16; ++i) { acc0[i] = 0.f; acc1[i] = 0.f; acc2[i] = 0.f; acc3[i] = 0.f; }
;   bf16* asw = As + lrow * LDT + lcc;
;   bf16* bsw = Bs + lrow * LDT + lcc;
;   const bf16* asr = As + (32 * w + r) * LDT + g * 8;
;   const bf16* bsr = Bs + r * LDT + g * 8;
;   for (int k0 = 0; k0 < K; k0 += 128) {
;     __syncthreads();
;     gt_store(t0, asw, bsw);
;     __syncthreads();
;     if (k0 + 128 < K) gt_load(t0, ap, bp, lda, ldb, KW(k0 + 128));
;     gt_compute(asr, bsr, acc0, acc1, acc2, acc3);
;     __syncthreads();
;     gt_store(t1, asw, bsw);
;     __syncthreads();
;     if (k0 + 192 < K) gt_load(t1, ap, bp, lda, ldb, KW(k0 + 192));
;     gt_compute(asr, bsr, acc0, acc1, acc2, acc3);
;   }
.Lmy_rss_q:
	s_or_b64 exec, exec, s[98:99]
	s_waitcnt lgkmcnt(0)
	s_barrier
	s_waitcnt vmcnt(13)
	ds_write_b128 v64, v[8:11]
	ds_write_b128 v64, v[0:3] offset:4608
	ds_write_b128 v64, v[4:7] offset:9216
	s_waitcnt vmcnt(11)
	ds_write_b128 v64, v[16:19] offset:13824
	ds_write_b128 v64, v[12:15] offset:18432
	s_waitcnt vmcnt(10)
	ds_write_b128 v64, v[20:23] offset:23040
	s_waitcnt vmcnt(9)
	ds_write_b128 v64, v[24:27] offset:27648
	s_waitcnt vmcnt(8)
	ds_write_b128 v64, v[28:31] offset:32256
	v_lshl_add_u64 v[0:1], v[76:77], 0, s[46:47]
	v_add_co_u32_e32 v4, vcc, s21, v0
	s_waitcnt lgkmcnt(0)
	s_nop 0
	v_addc_co_u32_e32 v5, vcc, 0, v1, vcc
	v_add_co_u32_e32 v6, vcc, s28, v0
	s_barrier
	s_nop 0
	v_addc_co_u32_e32 v7, vcc, 0, v1, vcc
	global_load_dwordx4 v[134:137], v[4:5], off offset:256
	global_load_dwordx4 v[138:141], v[6:7], off offset:256
	v_add_co_u32_e32 v4, vcc, s29, v0
	v_lshl_add_u64 v[2:3], v[78:79], 0, s[46:47]
	s_nop 0
	v_addc_co_u32_e32 v5, vcc, 0, v1, vcc
	global_load_dwordx4 v[142:145], v[0:1], off offset:256
	global_load_dwordx4 v[146:149], v[2:3], off offset:256
	v_add_co_u32_e32 v0, vcc, s34, v2
	s_nop 1
	v_addc_co_u32_e32 v1, vcc, 0, v3, vcc
	global_load_dwordx4 v[150:153], v[4:5], off offset:256
	global_load_dwordx4 v[154:157], v[0:1], off offset:256
	v_add_co_u32_e32 v0, vcc, s35, v2
	s_nop 1
	v_addc_co_u32_e32 v1, vcc, 0, v3, vcc
	v_add_co_u32_e32 v2, vcc, s38, v2
	s_nop 1
	v_addc_co_u32_e32 v3, vcc, 0, v3, vcc
	global_load_dwordx4 v[162:165], v[0:1], off offset:256
	global_load_dwordx4 v[166:169], v[2:3], off offset:256
	v_and_b32_e32 v1, 31, v40
	v_lshrrev_b32_e32 v0, 1, v40
	v_and_or_b32 v2, v0, s40, v1
	v_and_b32_e32 v0, 16, v0
	v_mad_u64_u32 v[66:67], s[46:47], v2, s39, v[0:1]
	v_mad_u32_u24 v65, v1, s39, v0
	ds_read_b128 v[0:3], v66
	ds_read_b128 v[170:173], v66 offset:32
	ds_read_b128 v[4:7], v65 offset:18432
	ds_read_b128 v[174:177], v65 offset:18464
	ds_read_b128 v[8:11], v65 offset:23040
	ds_read_b128 v[178:181], v65 offset:23072
	ds_read_b128 v[12:15], v65 offset:27648
	ds_read_b128 v[182:185], v65 offset:27680
	ds_read_b128 v[186:189], v65 offset:32256
	ds_read_b128 v[190:193], v65 offset:32288
	ds_read_b128 v[194:197], v66 offset:64
	ds_read_b128 v[198:201], v66 offset:96
	ds_read_b128 v[202:205], v65 offset:18496
	ds_read_b128 v[206:209], v65 offset:18528
	ds_read_b128 v[210:213], v65 offset:23104
	ds_read_b128 v[214:217], v65 offset:23136
	ds_read_b128 v[218:221], v65 offset:27712
	ds_read_b128 v[222:225], v65 offset:27744
	ds_read_b128 v[226:229], v65 offset:32320
	ds_read_b128 v[230:233], v65 offset:32352
	s_waitcnt lgkmcnt(14)
	v_mfma_f32_32x32x16_bf16 v[48:63], v[0:3], v[4:7], 0
	v_mfma_f32_32x32x16_bf16 v[32:47], v[0:3], v[8:11], 0
	s_waitcnt lgkmcnt(13)
	v_mfma_f32_32x32x16_bf16 v[16:31], v[0:3], v[12:15], 0
	s_waitcnt lgkmcnt(11)
	v_mfma_f32_32x32x16_bf16 v[0:15], v[0:3], v[186:189], 0
	v_mfma_f32_32x32x16_bf16 v[48:63], v[170:173], v[174:177], v[48:63]
	v_mfma_f32_32x32x16_bf16 v[32:47], v[170:173], v[178:181], v[32:47]
	v_mfma_f32_32x32x16_bf16 v[16:31], v[170:173], v[182:185], v[16:31]
	s_waitcnt lgkmcnt(10)
	v_mfma_f32_32x32x16_bf16 v[0:15], v[170:173], v[190:193], v[0:15]
	s_waitcnt lgkmcnt(7)
	v_mfma_f32_32x32x16_bf16 v[48:63], v[194:197], v[202:205], v[48:63]
	s_waitcnt lgkmcnt(5)
	v_mfma_f32_32x32x16_bf16 v[32:47], v[194:197], v[210:213], v[32:47]
	s_waitcnt lgkmcnt(3)
	v_mfma_f32_32x32x16_bf16 v[16:31], v[194:197], v[218:221], v[16:31]
	s_waitcnt lgkmcnt(1)
	v_mfma_f32_32x32x16_bf16 v[0:15], v[194:197], v[226:229], v[0:15]
	v_mfma_f32_32x32x16_bf16 v[48:63], v[198:201], v[206:209], v[48:63]
	v_mfma_f32_32x32x16_bf16 v[32:47], v[198:201], v[214:217], v[32:47]
	v_mfma_f32_32x32x16_bf16 v[16:31], v[198:201], v[222:225], v[16:31]
	s_waitcnt lgkmcnt(0)
	v_mfma_f32_32x32x16_bf16 v[0:15], v[198:201], v[230:233], v[0:15]
	s_cmp_lt_i32 s0, 3
	s_cselect_b32 s47, 0, -1
	s_cselect_b32 s46, 0, 0xfffffd00
	s_barrier
	s_waitcnt vmcnt(13)
	ds_write_b128 v64, v[88:91]
	ds_write_b128 v64, v[80:83] offset:4608
	ds_write_b128 v64, v[84:87] offset:9216
	s_waitcnt vmcnt(11)
	ds_write_b128 v64, v[96:99] offset:13824
	ds_write_b128 v64, v[92:95] offset:18432
	s_waitcnt vmcnt(10)
	ds_write_b128 v64, v[100:103] offset:23040
	s_waitcnt vmcnt(9)
	ds_write_b128 v64, v[124:127] offset:27648
	s_waitcnt vmcnt(8)
	ds_write_b128 v64, v[130:133] offset:32256
	v_lshl_add_u64 v[88:89], v[76:77], 0, s[46:47]
	v_add_co_u32_e32 v80, vcc, s21, v88
	v_lshl_add_u64 v[124:125], v[78:79], 0, s[46:47]
	s_nop 0
	v_addc_co_u32_e32 v81, vcc, 0, v89, vcc
	v_add_co_u32_e32 v84, vcc, s28, v88
	s_waitcnt lgkmcnt(0)
	s_nop 0
	v_addc_co_u32_e32 v85, vcc, 0, v89, vcc
	v_add_co_u32_e32 v96, vcc, s29, v88
	s_barrier
; #define MFMA(a, b, c) __builtin_amdgcn_mfma_f32_32x32x16_bf16((a), (b), (c), 0, 0, 0)
; DI void gt_compute(const bf16* asr, const bf16* bsr, f32x16& acc0, f32x16& acc1, f32x16& acc2, f32x16& acc3) {
;   bf16x8 a[4], b0[4], b1[4], b2[4], b3[4];
; #pragma unroll
;   for (int kk = 0; kk < 4; ++kk) {
;     a[kk] = *(const bf16x8*)(asr + kk * 16);
;     b0[kk] = *(const bf16x8*)(bsr + kk * 16);
;     b1[kk] = *(const bf16x8*)(bsr + 32 * LDT + kk * 16);
;     b2[kk] = *(const bf16x8*)(bsr + 64 * LDT + kk * 16);
;     b3[kk] = *(const bf16x8*)(bsr + 96 * LDT + kk * 16);
;   }
;   __builtin_amdgcn_sched_barrier(0);
;   __builtin_amdgcn_s_setprio(2);
; #pragma unroll
;   for (int kk = 0; kk < 4; ++kk) {
;     acc0 = MFMA(a[kk], b0[kk], acc0); acc1 = MFMA(a[kk], b1[kk], acc1); acc2 = MFMA(a[kk], b2[kk], acc2); acc3 = MFMA(a[kk], b3[kk], acc3);
;   }
;   __builtin_amdgcn_s_setprio(0);
;   __builtin_amdgcn_sched_barrier(0);
; }
; DI void gemm_mainloop(const bf16* __restrict__ A, int lda, const bf16* __restrict__ Bt, int ldb, int K, int m0, int n0,
;                       bf16* As, bf16* Bs, f32x16& acc0, f32x16& acc1, f32x16& acc2, f32x16& acc3) {
;   const int tid = opaque_tid(), lane = tid & 63, w = tid >> 6, r = lane & 31, g = lane >> 5;
;   const int lrow = tid >> 3, lcc = (tid & 7) * 8;
;   const bf16* ap = A + (size_t)(m0 + lrow) * lda + lcc;
;   const bf16* bp = Bt + (size_t)(n0 + lrow) * ldb + lcc;
;   GTile t0, t1;
;   asm volatile("" ::: "memory");
;   const int nkt = K >> 6;
;   int kb = ((((m0 >> 7) * 5 + (n0 >> 7) * 3) >> 1) % nkt) << 6;
;     ...
;   gt_load(t0, ap, bp, lda, ldb, KW(0));
;   gt_load(t1, ap, bp, lda, ldb, KW(64));
; #pragma unroll
;   for (int i = 0; i < 16; ++i) { acc0[i] = 0.f; acc1[i] = 0.f; acc2[i] = 0.f; acc3[i] = 0.f; }
;   bf16* asw = As + lrow * LDT + lcc;
;   bf16* bsw = Bs + lrow * LDT + lcc;
;   const bf16* asr = As + (32 * w + r) * LDT + g * 8;
;   const bf16* bsr = Bs + r * LDT + g * 8;
;   for (int k0 = 0; k0 < K; k0 += 128) {
;     __syncthreads();
;     gt_store(t0, asw, bsw);
;     __syncthreads();
;     if (k0 + 128 < K) gt_load(t0, ap, bp, lda, ldb, KW(k0 + 128));
;     gt_compute(asr, bsr, acc0, acc1, acc2, acc3);
;     __syncthreads();
;     gt_store(t1, asw, bsw);
;     __syncthreads();
;     if (k0 + 192 < K) gt_load(t1, ap, bp, lda, ldb, KW(k0 + 192));
;     gt_compute(asr, bsr, acc0, acc1, acc2, acc3);
;   }
	s_nop 0
	v_addc_co_u32_e32 v97, vcc, 0, v89, vcc
	v_add_co_u32_e32 v100, vcc, s34, v124
	s_nop 1
	v_addc_co_u32_e32 v101, vcc, 0, v125, vcc
	v_add_co_u32_e32 v126, vcc, s35, v124
	global_load_dwordx4 v[80:83], v[80:81], off offset:384
	s_nop 0
	global_load_dwordx4 v[84:87], v[84:85], off offset:384
	v_addc_co_u32_e32 v127, vcc, 0, v125, vcc
	v_add_co_u32_e32 v128, vcc, s38, v124
	global_load_dwordx4 v[88:91], v[88:89], off offset:384
	s_nop 0
	global_load_dwordx4 v[92:95], v[124:125], off offset:384
	s_nop 0
	global_load_dwordx4 v[96:99], v[96:97], off offset:384
	s_nop 0
	global_load_dwordx4 v[100:103], v[100:101], off offset:384
	v_addc_co_u32_e32 v129, vcc, 0, v125, vcc
	global_load_dwordx4 v[124:127], v[126:127], off offset:384
	s_nop 0
	global_load_dwordx4 v[130:133], v[128:129], off offset:384
	ds_read_b128 v[170:173], v66
	ds_read_b128 v[174:177], v66 offset:32
	ds_read_b128 v[178:181], v65 offset:18432
	ds_read_b128 v[182:185], v65 offset:18464
	ds_read_b128 v[186:189], v65 offset:23040
	ds_read_b128 v[190:193], v65 offset:23072
	ds_read_b128 v[194:197], v65 offset:27648
	ds_read_b128 v[198:201], v65 offset:27680
	ds_read_b128 v[202:205], v65 offset:32256
	ds_read_b128 v[206:209], v65 offset:32288
	ds_read_b128 v[210:213], v66 offset:64
	ds_read_b128 v[214:217], v66 offset:96
	ds_read_b128 v[218:221], v65 offset:18496
	ds_read_b128 v[222:225], v65 offset:18528
	ds_read_b128 v[226:229], v65 offset:23104
	ds_read_b128 v[230:233], v65 offset:23136
	ds_read_b128 v[234:237], v65 offset:27712
	ds_read_b128 v[238:241], v65 offset:27744
	ds_read_b128 v[242:245], v65 offset:32320
	ds_read_b128 v[246:249], v65 offset:32352
	s_waitcnt lgkmcnt(14)
	v_mfma_f32_32x32x16_bf16 v[48:63], v[170:173], v[178:181], v[48:63]
	v_mfma_f32_32x32x16_bf16 v[32:47], v[170:173], v[186:189], v[32:47]
	s_waitcnt lgkmcnt(13)
	v_mfma_f32_32x32x16_bf16 v[16:31], v[170:173], v[194:197], v[16:31]
	s_waitcnt lgkmcnt(11)
	v_mfma_f32_32x32x16_bf16 v[0:15], v[170:173], v[202:205], v[0:15]
	v_mfma_f32_32x32x16_bf16 v[48:63], v[174:177], v[182:185], v[48:63]
	v_mfma_f32_32x32x16_bf16 v[32:47], v[174:177], v[190:193], v[32:47]
	v_mfma_f32_32x32x16_bf16 v[16:31], v[174:177], v[198:201], v[16:31]
	s_waitcnt lgkmcnt(10)
	v_mfma_f32_32x32x16_bf16 v[0:15], v[174:177], v[206:209], v[0:15]
	s_waitcnt lgkmcnt(7)
	v_mfma_f32_32x32x16_bf16 v[48:63], v[210:213], v[218:221], v[48:63]
	s_waitcnt lgkmcnt(5)
	v_mfma_f32_32x32x16_bf16 v[32:47], v[210:213], v[226:229], v[32:47]
	s_waitcnt lgkmcnt(3)
	v_mfma_f32_32x32x16_bf16 v[16:31], v[210:213], v[234:237], v[16:31]
	s_waitcnt lgkmcnt(1)
	v_mfma_f32_32x32x16_bf16 v[0:15], v[210:213], v[242:245], v[0:15]
	v_mfma_f32_32x32x16_bf16 v[48:63], v[214:217], v[222:225], v[48:63]
	v_mfma_f32_32x32x16_bf16 v[32:47], v[214:217], v[230:233], v[32:47]
	v_mfma_f32_32x32x16_bf16 v[16:31], v[214:217], v[238:241], v[16:31]
	s_waitcnt lgkmcnt(0)
	v_mfma_f32_32x32x16_bf16 v[0:15], v[214:217], v[246:249], v[0:15]
	s_cmp_lt_i32 s0, 2
	s_cselect_b32 s47, 0, -1
	s_cselect_b32 s46, 0, 0xfffffd00
	v_lshl_add_u64 v[128:129], v[76:77], 0, s[46:47]
	s_barrier
	s_waitcnt vmcnt(13)
	ds_write_b128 v64, v[142:145]
	ds_write_b128 v64, v[134:137] offset:4608
	ds_write_b128 v64, v[138:141] offset:9216
	s_waitcnt vmcnt(11)
	ds_write_b128 v64, v[150:153] offset:13824
	ds_write_b128 v64, v[146:149] offset:18432
	s_waitcnt vmcnt(10)
	ds_write_b128 v64, v[154:157] offset:23040
	s_waitcnt vmcnt(9)
	ds_write_b128 v64, v[162:165] offset:27648
	s_waitcnt vmcnt(8)
	ds_write_b128 v64, v[166:169] offset:32256
	v_add_co_u32_e32 v134, vcc, s21, v128
	v_lshl_add_u64 v[162:163], v[78:79], 0, s[46:47]
	s_nop 0
	v_addc_co_u32_e32 v135, vcc, 0, v129, vcc
	v_add_co_u32_e32 v138, vcc, s28, v128
	s_waitcnt lgkmcnt(0)
	s_nop 0
	v_addc_co_u32_e32 v139, vcc, 0, v129, vcc
	v_add_co_u32_e32 v150, vcc, s29, v128
	s_barrier
	s_nop 0
	v_addc_co_u32_e32 v151, vcc, 0, v129, vcc
	global_load_dwordx4 v[134:137], v[134:135], off offset:512
	s_nop 0
	global_load_dwordx4 v[138:141], v[138:139], off offset:512
	s_nop 0
	global_load_dwordx4 v[142:145], v[128:129], off offset:512
	global_load_dwordx4 v[146:149], v[162:163], off offset:512
	v_add_co_u32_e32 v128, vcc, s34, v162
	s_nop 1
	v_addc_co_u32_e32 v129, vcc, 0, v163, vcc
	global_load_dwordx4 v[150:153], v[150:151], off offset:512
	s_nop 0
	global_load_dwordx4 v[154:157], v[128:129], off offset:512
	v_add_co_u32_e32 v128, vcc, s35, v162
	s_nop 1
	v_addc_co_u32_e32 v129, vcc, 0, v163, vcc
	v_add_co_u32_e32 v166, vcc, s38, v162
	s_nop 1
	v_addc_co_u32_e32 v167, vcc, 0, v163, vcc
	global_load_dwordx4 v[162:165], v[128:129], off offset:512
	s_nop 0
	global_load_dwordx4 v[166:169], v[166:167], off offset:512
	ds_read_b128 v[170:173], v66
	ds_read_b128 v[174:177], v66 offset:32
	ds_read_b128 v[178:181], v65 offset:18432
	ds_read_b128 v[182:185], v65 offset:18464
	ds_read_b128 v[186:189], v65 offset:23040
	ds_read_b128 v[190:193], v65 offset:23072
	ds_read_b128 v[194:197], v65 offset:27648
	ds_read_b128 v[198:201], v65 offset:27680
	ds_read_b128 v[202:205], v65 offset:32256
	ds_read_b128 v[206:209], v65 offset:32288
	ds_read_b128 v[210:213], v66 offset:64
	ds_read_b128 v[214:217], v66 offset:96
	ds_read_b128 v[218:221], v65 offset:18496
	ds_read_b128 v[222:225], v65 offset:18528
	ds_read_b128 v[226:229], v65 offset:23104
	ds_read_b128 v[230:233], v65 offset:23136
	ds_read_b128 v[234:237], v65 offset:27712
	ds_read_b128 v[238:241], v65 offset:27744
	ds_read_b128 v[242:245], v65 offset:32320
	ds_read_b128 v[246:249], v65 offset:32352
	s_waitcnt lgkmcnt(14)
	v_mfma_f32_32x32x16_bf16 v[48:63], v[170:173], v[178:181], v[48:63]
	v_mfma_f32_32x32x16_bf16 v[32:47], v[170:173], v[186:189], v[32:47]
	s_waitcnt lgkmcnt(13)
	v_mfma_f32_32x32x16_bf16 v[16:31], v[170:173], v[194:197], v[16:31]
	s_waitcnt lgkmcnt(11)
	v_mfma_f32_32x32x16_bf16 v[0:15], v[170:173], v[202:205], v[0:15]
	v_mfma_f32_32x32x16_bf16 v[48:63], v[174:177], v[182:185], v[48:63]
	v_mfma_f32_32x32x16_bf16 v[32:47], v[174:177], v[190:193], v[32:47]
	v_mfma_f32_32x32x16_bf16 v[16:31], v[174:177], v[198:201], v[16:31]
	s_waitcnt lgkmcnt(10)
	v_mfma_f32_32x32x16_bf16 v[0:15], v[174:177], v[206:209], v[0:15]
	s_waitcnt lgkmcnt(7)
	v_mfma_f32_32x32x16_bf16 v[48:63], v[210:213], v[218:221], v[48:63]
	s_waitcnt lgkmcnt(5)
	v_mfma_f32_32x32x16_bf16 v[32:47], v[210:213], v[226:229], v[32:47]
	s_waitcnt lgkmcnt(3)
	v_mfma_f32_32x32x16_bf16 v[16:31], v[210:213], v[234:237], v[16:31]
	s_waitcnt lgkmcnt(1)
	v_mfma_f32_32x32x16_bf16 v[0:15], v[210:213], v[242:245], v[0:15]
	v_mfma_f32_32x32x16_bf16 v[48:63], v[214:217], v[222:225], v[48:63]
	v_mfma_f32_32x32x16_bf16 v[32:47], v[214:217], v[230:233], v[32:47]
	v_mfma_f32_32x32x16_bf16 v[16:31], v[214:217], v[238:241], v[16:31]
	s_waitcnt lgkmcnt(0)
	v_mfma_f32_32x32x16_bf16 v[0:15], v[214:217], v[246:249], v[0:15]
	s_cmp_gt_i32 s0, 0
	s_cselect_b32 s1, -1, 0
	s_cselect_b32 s0, 0xfffffd00, 0
	s_barrier
; #define MFMA(a, b, c) __builtin_amdgcn_mfma_f32_32x32x16_bf16((a), (b), (c), 0, 0, 0)
; DI void gt_compute(const bf16* asr, const bf16* bsr, f32x16& acc0, f32x16& acc1, f32x16& acc2, f32x16& acc3) {
;   bf16x8 a[4], b0[4], b1[4], b2[4], b3[4];
; #pragma unroll
;   for (int kk = 0; kk < 4; ++kk) {
;     a[kk] = *(const bf16x8*)(asr + kk * 16);
;     b0[kk] = *(const bf16x8*)(bsr + kk * 16);
;     b1[kk] = *(const bf16x8*)(bsr + 32 * LDT + kk * 16);
;     b2[kk] = *(const bf16x8*)(bsr + 64 * LDT + kk * 16);
;     b3[kk] = *(const bf16x8*)(bsr + 96 * LDT + kk * 16);
;   }
;   __builtin_amdgcn_sched_barrier(0);
;   __builtin_amdgcn_s_setprio(2);
; #pragma unroll
;   for (int kk = 0; kk < 4; ++kk) {
;     acc0 = MFMA(a[kk], b0[kk], acc0); acc1 = MFMA(a[kk], b1[kk], acc1); acc2 = MFMA(a[kk], b2[kk], acc2); acc3 = MFMA(a[kk], b3[kk], acc3);
;   }
;   __builtin_amdgcn_s_setprio(0);
;   __builtin_amdgcn_sched_barrier(0);
; }
; DI void gemm_mainloop(const bf16* __restrict__ A, int lda, const bf16* __restrict__ Bt, int ldb, int K, int m0, int n0,
;                       bf16* As, bf16* Bs, f32x16& acc0, f32x16& acc1, f32x16& acc2, f32x16& acc3) {
;   const int tid = opaque_tid(), lane = tid & 63, w = tid >> 6, r = lane & 31, g = lane >> 5;
;   const int lrow = tid >> 3, lcc = (tid & 7) * 8;
;   const bf16* ap = A + (size_t)(m0 + lrow) * lda + lcc;
;   const bf16* bp = Bt + (size_t)(n0 + lrow) * ldb + lcc;
;   GTile t0, t1;
;   asm volatile("" ::: "memory");
;   const int nkt = K >> 6;
;   int kb = ((((m0 >> 7) * 5 + (n0 >> 7) * 3) >> 1) % nkt) << 6;
;     ...
;   gt_load(t0, ap, bp, lda, ldb, KW(0));
;   gt_load(t1, ap, bp, lda, ldb, KW(64));
; #pragma unroll
;   for (int i = 0; i < 16; ++i) { acc0[i] = 0.f; acc1[i] = 0.f; acc2[i] = 0.f; acc3[i] = 0.f; }
;   bf16* asw = As + lrow * LDT + lcc;
;   bf16* bsw = Bs + lrow * LDT + lcc;
;   const bf16* asr = As + (32 * w + r) * LDT + g * 8;
;   const bf16* bsr = Bs + r * LDT + g * 8;
;   for (int k0 = 0; k0 < K; k0 += 128) {
;     __syncthreads();
;     gt_store(t0, asw, bsw);
;     __syncthreads();
;     if (k0 + 128 < K) gt_load(t0, ap, bp, lda, ldb, KW(k0 + 128));
;     gt_compute(asr, bsr, acc0, acc1, acc2, acc3);
;     __syncthreads();
;     gt_store(t1, asw, bsw);
;     __syncthreads();
;     if (k0 + 192 < K) gt_load(t1, ap, bp, lda, ldb, KW(k0 + 192));
;     gt_compute(asr, bsr, acc0, acc1, acc2, acc3);
;   }
	s_waitcnt vmcnt(13)
	ds_write_b128 v64, v[88:91]
	ds_write_b128 v64, v[80:83] offset:4608
	ds_write_b128 v64, v[84:87] offset:9216
	s_waitcnt vmcnt(11)
	ds_write_b128 v64, v[96:99] offset:13824
	ds_write_b128 v64, v[92:95] offset:18432
	s_waitcnt vmcnt(10)
	ds_write_b128 v64, v[100:103] offset:23040
	s_waitcnt vmcnt(9)
	ds_write_b128 v64, v[124:127] offset:27648
	s_waitcnt vmcnt(8)
	ds_write_b128 v64, v[130:133] offset:32256
	v_lshl_add_u64 v[84:85], v[76:77], 0, s[0:1]
	v_add_co_u32_e32 v76, vcc, s21, v84
	v_lshl_add_u64 v[100:101], v[78:79], 0, s[0:1]
	s_nop 0
	v_addc_co_u32_e32 v77, vcc, 0, v85, vcc
	v_add_co_u32_e32 v80, vcc, s28, v84
	s_waitcnt lgkmcnt(0)
	s_nop 0
	v_addc_co_u32_e32 v81, vcc, 0, v85, vcc
	v_add_co_u32_e32 v92, vcc, s29, v84
	s_barrier
	s_nop 0
	v_addc_co_u32_e32 v93, vcc, 0, v85, vcc
	v_add_co_u32_e32 v96, vcc, s34, v100
	s_nop 1
	v_addc_co_u32_e32 v97, vcc, 0, v101, vcc
	v_add_co_u32_e32 v102, vcc, s35, v100
	global_load_dwordx4 v[76:79], v[76:77], off offset:640
	s_nop 0
	global_load_dwordx4 v[80:83], v[80:81], off offset:640
	v_addc_co_u32_e32 v103, vcc, 0, v101, vcc
	v_add_co_u32_e32 v124, vcc, s38, v100
	global_load_dwordx4 v[84:87], v[84:85], off offset:640
	s_nop 0
	global_load_dwordx4 v[88:91], v[100:101], off offset:640
	v_addc_co_u32_e32 v125, vcc, 0, v101, vcc
	global_load_dwordx4 v[92:95], v[92:93], off offset:640
	s_nop 0
	global_load_dwordx4 v[96:99], v[96:97], off offset:640
	s_nop 0
	global_load_dwordx4 v[100:103], v[102:103], off offset:640
	s_nop 0
	global_load_dwordx4 v[124:127], v[124:125], off offset:640
	ds_read_b128 v[130:133], v66
	ds_read_b128 v[170:173], v66 offset:32
	ds_read_b128 v[174:177], v65 offset:18432
	ds_read_b128 v[178:181], v65 offset:18464
	ds_read_b128 v[182:185], v65 offset:23040
	ds_read_b128 v[186:189], v65 offset:23072
	ds_read_b128 v[190:193], v65 offset:27648
	ds_read_b128 v[194:197], v65 offset:27680
	ds_read_b128 v[198:201], v65 offset:32256
	ds_read_b128 v[202:205], v65 offset:32288
	ds_read_b128 v[206:209], v66 offset:64
	ds_read_b128 v[210:213], v66 offset:96
	ds_read_b128 v[214:217], v65 offset:18496
	ds_read_b128 v[218:221], v65 offset:18528
	ds_read_b128 v[222:225], v65 offset:23104
	ds_read_b128 v[226:229], v65 offset:23136
	ds_read_b128 v[230:233], v65 offset:27712
	ds_read_b128 v[234:237], v65 offset:27744
	ds_read_b128 v[238:241], v65 offset:32320
	ds_read_b128 v[242:245], v65 offset:32352
	s_waitcnt lgkmcnt(14)
	v_mfma_f32_32x32x16_bf16 v[48:63], v[130:133], v[174:177], v[48:63]
	v_mfma_f32_32x32x16_bf16 v[32:47], v[130:133], v[182:185], v[32:47]
	s_waitcnt lgkmcnt(13)
	v_mfma_f32_32x32x16_bf16 v[16:31], v[130:133], v[190:193], v[16:31]
	s_waitcnt lgkmcnt(11)
	v_mfma_f32_32x32x16_bf16 v[0:15], v[130:133], v[198:201], v[0:15]
	v_mfma_f32_32x32x16_bf16 v[48:63], v[170:173], v[178:181], v[48:63]
	v_mfma_f32_32x32x16_bf16 v[32:47], v[170:173], v[186:189], v[32:47]
	v_mfma_f32_32x32x16_bf16 v[16:31], v[170:173], v[194:197], v[16:31]
	s_waitcnt lgkmcnt(10)
	v_mfma_f32_32x32x16_bf16 v[0:15], v[170:173], v[202:205], v[0:15]
	s_waitcnt lgkmcnt(7)
	v_mfma_f32_32x32x16_bf16 v[48:63], v[206:209], v[214:217], v[48:63]
	s_waitcnt lgkmcnt(5)
	v_mfma_f32_32x32x16_bf16 v[32:47], v[206:209], v[222:225], v[32:47]
	s_waitcnt lgkmcnt(3)
	v_mfma_f32_32x32x16_bf16 v[16:31], v[206:209], v[230:233], v[16:31]
	s_waitcnt lgkmcnt(1)
	v_mfma_f32_32x32x16_bf16 v[0:15], v[206:209], v[238:241], v[0:15]
	v_mfma_f32_32x32x16_bf16 v[48:63], v[210:213], v[218:221], v[48:63]
	v_mfma_f32_32x32x16_bf16 v[32:47], v[210:213], v[226:229], v[32:47]
	v_mfma_f32_32x32x16_bf16 v[16:31], v[210:213], v[234:237], v[16:31]
	s_waitcnt lgkmcnt(0)
	v_mfma_f32_32x32x16_bf16 v[0:15], v[210:213], v[242:245], v[0:15]
	s_barrier
	s_waitcnt vmcnt(13)
	ds_write_b128 v64, v[142:145]
	ds_write_b128 v64, v[134:137] offset:4608
	ds_write_b128 v64, v[138:141] offset:9216
	s_waitcnt vmcnt(11)
	ds_write_b128 v64, v[150:153] offset:13824
	ds_write_b128 v64, v[146:149] offset:18432
	s_waitcnt vmcnt(10)
	ds_write_b128 v64, v[154:157] offset:23040
	s_waitcnt vmcnt(9)
	ds_write_b128 v64, v[162:165] offset:27648
	s_waitcnt vmcnt(8)
	ds_write_b128 v64, v[166:169] offset:32256
	s_waitcnt lgkmcnt(0)
	s_barrier
	ds_read_b128 v[130:133], v66
	ds_read_b128 v[134:137], v66 offset:32
	ds_read_b128 v[138:141], v65 offset:18432
	ds_read_b128 v[142:145], v65 offset:18464
	ds_read_b128 v[146:149], v65 offset:23040
	ds_read_b128 v[150:153], v65 offset:23072
	ds_read_b128 v[154:157], v65 offset:27648
	ds_read_b128 v[162:165], v65 offset:27680
	ds_read_b128 v[166:169], v65 offset:32256
	ds_read_b128 v[170:173], v65 offset:32288
	ds_read_b128 v[174:177], v66 offset:64
	ds_read_b128 v[178:181], v66 offset:96
	ds_read_b128 v[182:185], v65 offset:18496
	ds_read_b128 v[186:189], v65 offset:18528
	ds_read_b128 v[190:193], v65 offset:23104
	ds_read_b128 v[194:197], v65 offset:23136
	ds_read_b128 v[198:201], v65 offset:27712
	ds_read_b128 v[202:205], v65 offset:27744
	ds_read_b128 v[206:209], v65 offset:32320
	ds_read_b128 v[210:213], v65 offset:32352
	s_waitcnt lgkmcnt(14)
	v_mfma_f32_32x32x16_bf16 v[48:63], v[130:133], v[138:141], v[48:63]
	v_mfma_f32_32x32x16_bf16 v[32:47], v[130:133], v[146:149], v[32:47]
	s_waitcnt lgkmcnt(13)
	v_mfma_f32_32x32x16_bf16 v[16:31], v[130:133], v[154:157], v[16:31]
	s_waitcnt lgkmcnt(11)
	v_mfma_f32_32x32x16_bf16 v[0:15], v[130:133], v[166:169], v[0:15]
	v_mfma_f32_32x32x16_bf16 v[48:63], v[134:137], v[142:145], v[48:63]
	v_mfma_f32_32x32x16_bf16 v[32:47], v[134:137], v[150:153], v[32:47]
	v_mfma_f32_32x32x16_bf16 v[16:31], v[134:137], v[162:165], v[16:31]
	s_waitcnt lgkmcnt(10)
	v_mfma_f32_32x32x16_bf16 v[0:15], v[134:137], v[170:173], v[0:15]
	s_waitcnt lgkmcnt(7)
	v_mfma_f32_32x32x16_bf16 v[48:63], v[174:177], v[182:185], v[48:63]
	s_waitcnt lgkmcnt(5)
	v_mfma_f32_32x32x16_bf16 v[32:47], v[174:177], v[190:193], v[32:47]
	s_waitcnt lgkmcnt(3)
	v_mfma_f32_32x32x16_bf16 v[16:31], v[174:177], v[198:201], v[16:31]
	s_waitcnt lgkmcnt(1)
	v_mfma_f32_32x32x16_bf16 v[0:15], v[174:177], v[206:209], v[0:15]
	v_mfma_f32_32x32x16_bf16 v[48:63], v[178:181], v[186:189], v[48:63]
	v_mfma_f32_32x32x16_bf16 v[32:47], v[178:181], v[194:197], v[32:47]
	v_mfma_f32_32x32x16_bf16 v[16:31], v[178:181], v[202:205], v[16:31]
	s_waitcnt lgkmcnt(0)
	v_mfma_f32_32x32x16_bf16 v[0:15], v[178:181], v[210:213], v[0:15]
	s_barrier
; #define MFMA(a, b, c) __builtin_amdgcn_mfma_f32_32x32x16_bf16((a), (b), (c), 0, 0, 0)
; DI bf16 f2bf(float a) { return (bf16)(pack2(a, 0.f) & 0xffffu); }
; DI int crow(int i, int g) { return (i & 3) + 8 * (i >> 2) + 4 * g; }
; DI void gt_compute(const bf16* asr, const bf16* bsr, f32x16& acc0, f32x16& acc1, f32x16& acc2, f32x16& acc3) {
;   bf16x8 a[4], b0[4], b1[4], b2[4], b3[4];
; #pragma unroll
;   for (int kk = 0; kk < 4; ++kk) {
;     a[kk] = *(const bf16x8*)(asr + kk * 16);
;     b0[kk] = *(const bf16x8*)(bsr + kk * 16);
;     b1[kk] = *(const bf16x8*)(bsr + 32 * LDT + kk * 16);
;     b2[kk] = *(const bf16x8*)(bsr + 64 * LDT + kk * 16);
;     b3[kk] = *(const bf16x8*)(bsr + 96 * LDT + kk * 16);
;   }
;   __builtin_amdgcn_sched_barrier(0);
;   __builtin_amdgcn_s_setprio(2);
; #pragma unroll
;   for (int kk = 0; kk < 4; ++kk) {
;     acc0 = MFMA(a[kk], b0[kk], acc0); acc1 = MFMA(a[kk], b1[kk], acc1); acc2 = MFMA(a[kk], b2[kk], acc2); acc3 = MFMA(a[kk], b3[kk], acc3);
;   }
;   __builtin_amdgcn_s_setprio(0);
;   __builtin_amdgcn_sched_barrier(0);
; }
;     ...
;     } else if constexpr (EPI == EPI_MLA_Q) {
;       bf16* Qb = (bf16*)(ws + OFF_Q);
;       const float2* t64 = (const float2*)(ws + OFF_TAB64);
;       __syncthreads();
; #pragma unroll
;       for (int j = 0; j < 4; ++j) {
;         const int n = n0 + 32 * j;
;         const int hh = n / 192, d0 = n % 192;
;         if (d0 < 128) {
; #pragma unroll
;           for (int i = 0; i < 16; ++i) {
;             int rl = 32 * w + crow(i, g);
;             int s = (m0 & 2047) + rl;
;             Qb[((size_t)(bidx * 8 + hh) * 2048 + s) * 192 + d0 + r] = f2bf(acc[j][i] * rs[rl]);
;           }
;         } else if (d0 == 128) {
;           if (j < 3) {
; #pragma unroll
;             for (int i = 0; i < 16; ++i) {
;               int rl = 32 * w + crow(i, g);
;               int s = (m0 & 2047) + rl;
;               float2 cs = t64[s * 32 + r];
;               float x1 = acc[j][i] * rs[rl], x2 = acc[(j + 1) & 3][i] * rs[rl];
	s_waitcnt vmcnt(5)
	ds_write_b128 v64, v[84:87]
	ds_write_b128 v64, v[76:79] offset:4608
	ds_write_b128 v64, v[80:83] offset:9216
	s_waitcnt vmcnt(3)
	ds_write_b128 v64, v[92:95] offset:13824
	ds_write_b128 v64, v[88:91] offset:18432
	s_waitcnt vmcnt(2)
	ds_write_b128 v64, v[96:99] offset:23040
	s_waitcnt vmcnt(1)
	ds_write_b128 v64, v[100:103] offset:27648
	s_waitcnt vmcnt(0)
	ds_write_b128 v64, v[124:127] offset:32256
	s_waitcnt lgkmcnt(0)
	s_barrier
	ds_read_b128 v[76:79], v66
	ds_read_b128 v[80:83], v66 offset:32
	ds_read_b128 v[84:87], v65 offset:18432
	ds_read_b128 v[88:91], v65 offset:18464
	ds_read_b128 v[92:95], v65 offset:23040
	ds_read_b128 v[96:99], v65 offset:23072
	ds_read_b128 v[100:103], v65 offset:27648
	ds_read_b128 v[124:127], v65 offset:27680
	ds_read_b128 v[130:133], v65 offset:32256
	ds_read_b128 v[134:137], v65 offset:32288
	ds_read_b128 v[138:141], v66 offset:64
	ds_read_b128 v[142:145], v66 offset:96
	ds_read_b128 v[146:149], v65 offset:18496
	ds_read_b128 v[150:153], v65 offset:18528
	ds_read_b128 v[154:157], v65 offset:23104
	ds_read_b128 v[162:165], v65 offset:23136
	ds_read_b128 v[166:169], v65 offset:27712
	ds_read_b128 v[170:173], v65 offset:27744
	ds_read_b128 v[174:177], v65 offset:32320
	ds_read_b128 v[64:67], v65 offset:32352
	s_waitcnt lgkmcnt(14)
	v_mfma_f32_32x32x16_bf16 v[48:63], v[76:79], v[84:87], v[48:63]
	v_mfma_f32_32x32x16_bf16 v[32:47], v[76:79], v[92:95], v[32:47]
	s_waitcnt lgkmcnt(13)
	v_mfma_f32_32x32x16_bf16 v[16:31], v[76:79], v[100:103], v[16:31]
	s_waitcnt lgkmcnt(11)
	v_mfma_f32_32x32x16_bf16 v[0:15], v[76:79], v[130:133], v[0:15]
	v_mfma_f32_32x32x16_bf16 v[48:63], v[80:83], v[88:91], v[48:63]
	v_mfma_f32_32x32x16_bf16 v[32:47], v[80:83], v[96:99], v[32:47]
	v_mfma_f32_32x32x16_bf16 v[16:31], v[80:83], v[124:127], v[16:31]
	s_waitcnt lgkmcnt(10)
	v_mfma_f32_32x32x16_bf16 v[0:15], v[80:83], v[134:137], v[0:15]
	s_waitcnt lgkmcnt(7)
	v_mfma_f32_32x32x16_bf16 v[48:63], v[138:141], v[146:149], v[48:63]
	s_waitcnt lgkmcnt(5)
	v_mfma_f32_32x32x16_bf16 v[32:47], v[138:141], v[154:157], v[32:47]
	s_waitcnt lgkmcnt(3)
	v_mfma_f32_32x32x16_bf16 v[16:31], v[138:141], v[166:169], v[16:31]
	s_waitcnt lgkmcnt(1)
	v_mfma_f32_32x32x16_bf16 v[0:15], v[138:141], v[174:177], v[0:15]
	v_mfma_f32_32x32x16_bf16 v[48:63], v[142:145], v[150:153], v[48:63]
	v_mfma_f32_32x32x16_bf16 v[32:47], v[142:145], v[162:165], v[32:47]
	v_mfma_f32_32x32x16_bf16 v[16:31], v[142:145], v[170:173], v[16:31]
	s_waitcnt lgkmcnt(0)
	v_mfma_f32_32x32x16_bf16 v[0:15], v[142:145], v[64:67], v[0:15]
	s_ashr_i32 s0, s14, 1
	s_and_b32 s45, s0, -8
	s_mul_i32 s0, s12, 0x2aab
	s_lshr_b32 s1, s0, 31
	s_ashr_i32 s13, s0, 21
	s_add_i32 s13, s13, s1
	s_mul_i32 s0, s13, 0xc0
	s_sub_i32 s0, s12, s0
	s_and_b32 s46, s15, 0x780
	s_sext_i32_i16 s12, s0
	s_cmpk_gt_i32 s12, 0x7f
	s_mov_b64 s[14:15], -1
	s_barrier
	s_cbranch_scc0 .LBB0_329
	s_and_b32 s0, 0xffff, s0
	s_cmpk_lg_i32 s0, 0x80
	s_cbranch_scc1 .LBB0_328
	v_add_u32_e32 v80, s46, v107
	v_lshl_or_b32 v64, v80, 5, v105
	v_ashrrev_i32_e32 v65, 31, v64
	v_lshl_add_u64 v[64:65], v[64:65], 3, s[10:11]
	global_load_dwordx2 v[82:83], v[64:65], off
	v_add_u32_e32 v232, s46, v109
	v_lshl_or_b32 v232, v232, 5, v105
	v_mov_b32_e32 v233, 0
	v_lshl_add_u64 v[232:233], v[232:233], 3, s[10:11]
	global_load_dwordx2 v[202:203], v[232:233], off
	v_add_u32_e32 v234, s46, v110
	v_lshl_or_b32 v234, v234, 5, v105
	v_mov_b32_e32 v235, 0
	v_lshl_add_u64 v[234:235], v[234:235], 3, s[10:11]
	global_load_dwordx2 v[204:205], v[234:235], off
	v_add_u32_e32 v232, s46, v111
	v_lshl_or_b32 v232, v232, 5, v105
	v_mov_b32_e32 v233, 0
	v_lshl_add_u64 v[232:233], v[232:233], 3, s[10:11]
	global_load_dwordx2 v[206:207], v[232:233], off
	v_add_u32_e32 v234, s46, v112
	v_lshl_or_b32 v234, v234, 5, v105
	v_mov_b32_e32 v235, 0
	v_lshl_add_u64 v[234:235], v[234:235], 3, s[10:11]
	global_load_dwordx2 v[208:209], v[234:235], off
	v_add_u32_e32 v232, s46, v113
	v_lshl_or_b32 v232, v232, 5, v105
	v_mov_b32_e32 v233, 0
	v_lshl_add_u64 v[232:233], v[232:233], 3, s[10:11]
	global_load_dwordx2 v[210:211], v[232:233], off
	v_add_u32_e32 v234, s46, v114
	v_lshl_or_b32 v234, v234, 5, v105
	v_mov_b32_e32 v235, 0
	v_lshl_add_u64 v[234:235], v[234:235], 3, s[10:11]
	global_load_dwordx2 v[212:213], v[234:235], off
	v_add_u32_e32 v232, s46, v115
	v_lshl_or_b32 v232, v232, 5, v105
	v_mov_b32_e32 v233, 0
	v_lshl_add_u64 v[232:233], v[232:233], 3, s[10:11]
	global_load_dwordx2 v[214:215], v[232:233], off
	v_add_u32_e32 v234, s46, v116
	v_lshl_or_b32 v234, v234, 5, v105
	v_mov_b32_e32 v235, 0
	v_lshl_add_u64 v[234:235], v[234:235], 3, s[10:11]
	global_load_dwordx2 v[216:217], v[234:235], off
	v_add_u32_e32 v232, s46, v117
	v_lshl_or_b32 v232, v232, 5, v105
	v_mov_b32_e32 v233, 0
	v_lshl_add_u64 v[232:233], v[232:233], 3, s[10:11]
	global_load_dwordx2 v[218:219], v[232:233], off
	v_add_u32_e32 v234, s46, v118
	v_lshl_or_b32 v234, v234, 5, v105
	v_mov_b32_e32 v235, 0
	v_lshl_add_u64 v[234:235], v[234:235], 3, s[10:11]
	global_load_dwordx2 v[220:221], v[234:235], off
	v_add_u32_e32 v232, s46, v119
	v_lshl_or_b32 v232, v232, 5, v105
	v_mov_b32_e32 v233, 0
	v_lshl_add_u64 v[232:233], v[232:233], 3, s[10:11]
	global_load_dwordx2 v[222:223], v[232:233], off
	v_add_u32_e32 v234, s46, v120
	v_lshl_or_b32 v234, v234, 5, v105
	v_mov_b32_e32 v235, 0
	v_lshl_add_u64 v[234:235], v[234:235], 3, s[10:11]
	global_load_dwordx2 v[224:225], v[234:235], off
	v_add_u32_e32 v232, s46, v121
	v_lshl_or_b32 v232, v232, 5, v105
	v_mov_b32_e32 v233, 0
	v_lshl_add_u64 v[232:233], v[232:233], 3, s[10:11]
	global_load_dwordx2 v[226:227], v[232:233], off
	v_add_u32_e32 v234, s46, v122
	v_lshl_or_b32 v234, v234, 5, v105
	v_mov_b32_e32 v235, 0
	v_lshl_add_u64 v[234:235], v[234:235], 3, s[10:11]
	global_load_dwordx2 v[228:229], v[234:235], off
	v_add_u32_e32 v232, s46, v123
	v_lshl_or_b32 v232, v232, 5, v105
	v_mov_b32_e32 v233, 0
	v_lshl_add_u64 v[232:233], v[232:233], 3, s[10:11]
	global_load_dwordx2 v[230:231], v[232:233], off
	ds_read_b128 v[76:79], v108 offset:40960
	ds_read_b128 v[64:67], v108 offset:40992
	s_add_i32 s0, s45, s13
	s_ashr_i32 s1, s0, 31
	v_ashrrev_i32_e32 v81, 31, v80
	s_lshl_b64 s[14:15], s[0:1], 11
	v_lshl_add_u64 v[80:81], s[14:15], 0, v[80:81]
	s_waitcnt lgkmcnt(1)
; DI bf16 f2bf(float a) { return (bf16)(pack2(a, 0.f) & 0xffffu); }
; DI int crow(int i, int g) { return (i & 3) + 8 * (i >> 2) + 4 * g; }
;     ...
;           if (j < 3) {
; #pragma unroll
;             for (int i = 0; i < 16; ++i) {
;               int rl = 32 * w + crow(i, g);
;               int s = (m0 & 2047) + rl;
;               float2 cs = t64[s * 32 + r];
;               float x1 = acc[j][i] * rs[rl], x2 = acc[(j + 1) & 3][i] * rs[rl];
;               bf16* qp = Qb + ((size_t)(bidx * 8 + hh) * 2048 + s) * 192 + 128;
;               qp[r] = f2bf(x1 * cs.x - x2 * cs.y);
;               qp[32 + r] = f2bf(x2 * cs.x + x1 * cs.y);
;             }
	v_mul_f32_e32 v68, v48, v76
	v_mul_f32_e32 v76, v32, v76
	v_add_u32_e32 v84, s46, v109
	v_mad_u64_u32 v[88:89], s[0:1], v80, s41, v[70:71]
	v_lshl_or_b32 v86, v84, 5, v105
	v_ashrrev_i32_e32 v87, 31, v86
	v_mad_i32_i24 v89, v81, s41, v89
	v_lshl_add_u64 v[86:87], v[86:87], 3, s[10:11]
	v_ashrrev_i32_e32 v85, 31, v84
	v_lshl_add_u64 v[84:85], s[14:15], 0, v[84:85]
	s_waitcnt vmcnt(0)
	v_mul_f32_e32 v80, v83, v76
	v_mul_f32_e32 v76, v82, v76
	v_fma_f32 v80, v82, v68, -v80
	v_fmac_f32_e32 v76, v83, v68
	v_cvt_pk_bf16_f32 v68, v80, s0
	v_cvt_pk_bf16_f32 v76, v76, s0
	global_store_short v[88:89], v68, off offset:256
	global_store_short v[88:89], v76, off offset:320
	v_mov_b32_e32 v80, v202
	v_mov_b32_e32 v81, v203
	v_mul_f32_e32 v68, v49, v77
	v_mul_f32_e32 v77, v33, v77
	v_add_u32_e32 v76, s46, v110
	v_mad_u64_u32 v[86:87], s[0:1], v84, s41, v[70:71]
	v_lshl_or_b32 v82, v76, 5, v105
	v_ashrrev_i32_e32 v83, 31, v82
	v_mad_i32_i24 v87, v85, s41, v87
	v_lshl_add_u64 v[82:83], v[82:83], 3, s[10:11]
	v_mul_f32_e32 v84, v81, v77
	v_mul_f32_e32 v77, v80, v77
	v_fma_f32 v80, v80, v68, -v84
	v_fmac_f32_e32 v77, v81, v68
	v_cvt_pk_bf16_f32 v68, v80, s0
	v_cvt_pk_bf16_f32 v77, v77, s0
	global_store_short v[86:87], v68, off offset:256
	global_store_short v[86:87], v77, off offset:320
	v_mov_b32_e32 v80, v204
	v_mov_b32_e32 v81, v205
	v_ashrrev_i32_e32 v77, 31, v76
	v_lshl_add_u64 v[76:77], s[14:15], 0, v[76:77]
	v_mad_u64_u32 v[86:87], s[0:1], v76, s41, v[70:71]
	v_mul_f32_e32 v76, v34, v78
	v_add_u32_e32 v82, s46, v111
	v_mul_f32_e32 v68, v50, v78
	v_mad_i32_i24 v87, v77, s41, v87
	v_lshl_or_b32 v84, v82, 5, v105
	v_ashrrev_i32_e32 v85, 31, v84
	v_lshl_add_u64 v[84:85], v[84:85], 3, s[10:11]
	v_ashrrev_i32_e32 v83, 31, v82
	v_lshl_add_u64 v[82:83], s[14:15], 0, v[82:83]
	v_add_u32_e32 v78, s46, v112
	v_mul_f32_e32 v77, v81, v76
	v_mul_f32_e32 v76, v80, v76
	v_fma_f32 v77, v80, v68, -v77
	v_fmac_f32_e32 v76, v81, v68
	v_cvt_pk_bf16_f32 v68, v77, s0
	v_cvt_pk_bf16_f32 v76, v76, s0
	global_store_short v[86:87], v68, off offset:256
	global_store_short v[86:87], v76, off offset:320
	v_mov_b32_e32 v76, v206
	v_mov_b32_e32 v77, v207
	v_mul_f32_e32 v68, v51, v79
	v_mul_f32_e32 v79, v35, v79
	v_mad_u64_u32 v[84:85], s[0:1], v82, s41, v[70:71]
	v_lshl_or_b32 v80, v78, 5, v105
	v_ashrrev_i32_e32 v81, 31, v80
	v_mad_i32_i24 v85, v83, s41, v85
	v_lshl_add_u64 v[80:81], v[80:81], 3, s[10:11]
	v_mul_f32_e32 v82, v77, v79
	v_mul_f32_e32 v79, v76, v79
	v_fma_f32 v76, v76, v68, -v82
	v_fmac_f32_e32 v79, v77, v68
	v_cvt_pk_bf16_f32 v68, v76, s0
	v_cvt_pk_bf16_f32 v76, v79, s0
	global_store_short v[84:85], v68, off offset:256
	global_store_short v[84:85], v76, off offset:320
	v_mov_b32_e32 v76, v208
	v_mov_b32_e32 v77, v209
	v_ashrrev_i32_e32 v79, 31, v78
	v_lshl_add_u64 v[78:79], s[14:15], 0, v[78:79]
	s_waitcnt lgkmcnt(0)
	v_mul_f32_e32 v68, v52, v64
	v_mul_f32_e32 v64, v36, v64
	v_add_u32_e32 v80, s46, v113
	v_mad_u64_u32 v[84:85], s[0:1], v78, s41, v[70:71]
	v_lshl_or_b32 v82, v80, 5, v105
	v_ashrrev_i32_e32 v83, 31, v82
	v_mad_i32_i24 v85, v79, s41, v85
	v_lshl_add_u64 v[82:83], v[82:83], 3, s[10:11]
	v_ashrrev_i32_e32 v81, 31, v80
	v_lshl_add_u64 v[80:81], s[14:15], 0, v[80:81]
	v_mul_f32_e32 v78, v77, v64
	v_mul_f32_e32 v64, v76, v64
	v_fma_f32 v76, v76, v68, -v78
	v_fmac_f32_e32 v64, v77, v68
	v_cvt_pk_bf16_f32 v68, v76, s0
	v_cvt_pk_bf16_f32 v64, v64, s0
	global_store_short v[84:85], v68, off offset:256
	global_store_short v[84:85], v64, off offset:320
	v_mov_b32_e32 v76, v210
	v_mov_b32_e32 v77, v211
	v_mul_f32_e32 v68, v53, v65
	v_mul_f32_e32 v65, v37, v65
	v_add_u32_e32 v64, s46, v114
	v_mad_u64_u32 v[82:83], s[0:1], v80, s41, v[70:71]
	v_lshl_or_b32 v78, v64, 5, v105
	v_ashrrev_i32_e32 v79, 31, v78
	v_mad_i32_i24 v83, v81, s41, v83
	v_lshl_add_u64 v[78:79], v[78:79], 3, s[10:11]
	v_add_u32_e32 v84, s46, v117
	v_lshl_or_b32 v86, v84, 5, v105
	v_ashrrev_i32_e32 v87, 31, v86
	v_lshl_add_u64 v[86:87], v[86:87], 3, s[10:11]
	v_ashrrev_i32_e32 v85, 31, v84
	v_lshl_add_u64 v[84:85], s[14:15], 0, v[84:85]
	v_mul_f32_e32 v80, v77, v65
	v_mul_f32_e32 v65, v76, v65
	v_fma_f32 v76, v76, v68, -v80
	v_fmac_f32_e32 v65, v77, v68
	v_cvt_pk_bf16_f32 v68, v76, s0
	v_cvt_pk_bf16_f32 v65, v65, s0
	global_store_short v[82:83], v68, off offset:256
	global_store_short v[82:83], v65, off offset:320
	v_mov_b32_e32 v76, v212
	v_mov_b32_e32 v77, v213
	v_ashrrev_i32_e32 v65, 31, v64
	v_lshl_add_u64 v[64:65], s[14:15], 0, v[64:65]
	v_mad_u64_u32 v[82:83], s[0:1], v64, s41, v[70:71]
	v_mul_f32_e32 v64, v54, v66
	v_mul_f32_e32 v66, v38, v66
	v_add_u32_e32 v78, s46, v115
	v_mad_i32_i24 v83, v65, s41, v83
	v_lshl_or_b32 v80, v78, 5, v105
	v_ashrrev_i32_e32 v81, 31, v80
	v_lshl_add_u64 v[80:81], v[80:81], 3, s[10:11]
	v_ashrrev_i32_e32 v79, 31, v78
	v_lshl_add_u64 v[78:79], s[14:15], 0, v[78:79]
	v_mul_f32_e32 v65, v77, v66
	v_mul_f32_e32 v66, v76, v66
	v_fma_f32 v65, v76, v64, -v65
	v_fmac_f32_e32 v66, v77, v64
	v_cvt_pk_bf16_f32 v64, v65, s0
	v_cvt_pk_bf16_f32 v65, v66, s0
	global_store_short v[82:83], v64, off offset:256
	global_store_short v[82:83], v65, off offset:320
	v_mov_b32_e32 v64, v214
	v_mov_b32_e32 v65, v215
	v_mul_f32_e32 v66, v55, v67
	v_mul_f32_e32 v67, v39, v67
	v_add_u32_e32 v80, s46, v116
	v_lshl_or_b32 v76, v80, 5, v105
	v_mad_u64_u32 v[82:83], s[0:1], v78, s41, v[70:71]
	v_ashrrev_i32_e32 v77, 31, v76
	v_mad_i32_i24 v83, v79, s41, v83
	v_lshl_add_u64 v[76:77], v[76:77], 3, s[10:11]
	v_ashrrev_i32_e32 v81, 31, v80
	v_lshl_add_u64 v[80:81], s[14:15], 0, v[80:81]
	v_mul_f32_e32 v68, v65, v67
	v_mul_f32_e32 v67, v64, v67
	v_fma_f32 v64, v64, v66, -v68
	v_fmac_f32_e32 v67, v65, v66
	v_cvt_pk_bf16_f32 v64, v64, s0
	v_cvt_pk_bf16_f32 v65, v67, s0
	global_store_short v[82:83], v64, off offset:256
	global_store_short v[82:83], v65, off offset:320
	v_mov_b32_e32 v82, v216
	v_mov_b32_e32 v83, v217
	ds_read_b128 v[64:67], v108 offset:41024
	ds_read_b128 v[76:79], v108 offset:41056
	v_mad_u64_u32 v[88:89], s[0:1], v80, s41, v[70:71]
	v_mad_i32_i24 v89, v81, s41, v89
	s_waitcnt lgkmcnt(1)
; DI bf16 f2bf(float a) { return (bf16)(pack2(a, 0.f) & 0xffffu); }
; DI int crow(int i, int g) { return (i & 3) + 8 * (i >> 2) + 4 * g; }
;     ...
;           if (j < 3) {
; #pragma unroll
;             for (int i = 0; i < 16; ++i) {
;               int rl = 32 * w + crow(i, g);
;               int s = (m0 & 2047) + rl;
;               float2 cs = t64[s * 32 + r];
;               float x1 = acc[j][i] * rs[rl], x2 = acc[(j + 1) & 3][i] * rs[rl];
;               bf16* qp = Qb + ((size_t)(bidx * 8 + hh) * 2048 + s) * 192 + 128;
;               qp[r] = f2bf(x1 * cs.x - x2 * cs.y);
;               qp[32 + r] = f2bf(x2 * cs.x + x1 * cs.y);
;             }
	v_mul_f32_e32 v68, v56, v64
	v_mul_f32_e32 v64, v40, v64
	v_mul_f32_e32 v80, v83, v64
	v_mul_f32_e32 v64, v82, v64
	v_fma_f32 v80, v82, v68, -v80
	v_fmac_f32_e32 v64, v83, v68
	v_cvt_pk_bf16_f32 v68, v80, s0
	v_cvt_pk_bf16_f32 v64, v64, s0
	global_store_short v[88:89], v68, off offset:256
	global_store_short v[88:89], v64, off offset:320
	v_mov_b32_e32 v80, v218
	v_mov_b32_e32 v81, v219
	v_mul_f32_e32 v68, v57, v65
	v_mul_f32_e32 v65, v41, v65
	v_add_u32_e32 v64, s46, v118
	v_mad_u64_u32 v[86:87], s[0:1], v84, s41, v[70:71]
	v_lshl_or_b32 v82, v64, 5, v105
	v_ashrrev_i32_e32 v83, 31, v82
	v_mad_i32_i24 v87, v85, s41, v87
	v_lshl_add_u64 v[82:83], v[82:83], 3, s[10:11]
	v_mul_f32_e32 v84, v81, v65
	v_mul_f32_e32 v65, v80, v65
	v_fma_f32 v80, v80, v68, -v84
	v_fmac_f32_e32 v65, v81, v68
	v_cvt_pk_bf16_f32 v68, v80, s0
	v_cvt_pk_bf16_f32 v65, v65, s0
	global_store_short v[86:87], v68, off offset:256
	global_store_short v[86:87], v65, off offset:320
	v_mov_b32_e32 v80, v220
	v_mov_b32_e32 v81, v221
	v_ashrrev_i32_e32 v65, 31, v64
	v_lshl_add_u64 v[64:65], s[14:15], 0, v[64:65]
	v_mad_u64_u32 v[86:87], s[0:1], v64, s41, v[70:71]
	v_mul_f32_e32 v64, v58, v66
	v_mul_f32_e32 v66, v42, v66
	v_add_u32_e32 v82, s46, v119
	v_mad_i32_i24 v87, v65, s41, v87
	v_lshl_or_b32 v84, v82, 5, v105
	v_ashrrev_i32_e32 v85, 31, v84
	v_lshl_add_u64 v[84:85], v[84:85], 3, s[10:11]
	v_ashrrev_i32_e32 v83, 31, v82
	v_lshl_add_u64 v[82:83], s[14:15], 0, v[82:83]
	v_mul_f32_e32 v68, v59, v67
	v_mul_f32_e32 v67, v43, v67
	v_mul_f32_e32 v65, v81, v66
	v_mul_f32_e32 v66, v80, v66
	v_fma_f32 v65, v80, v64, -v65
	v_fmac_f32_e32 v66, v81, v64
	v_cvt_pk_bf16_f32 v64, v65, s0
	v_cvt_pk_bf16_f32 v65, v66, s0
	global_store_short v[86:87], v64, off offset:256
	global_store_short v[86:87], v65, off offset:320
	v_mov_b32_e32 v64, v222
	v_mov_b32_e32 v65, v223
	v_add_u32_e32 v66, s46, v120
	v_mad_u64_u32 v[84:85], s[0:1], v82, s41, v[70:71]
	v_lshl_or_b32 v80, v66, 5, v105
	v_ashrrev_i32_e32 v81, 31, v80
	v_mad_i32_i24 v85, v83, s41, v85
	v_lshl_add_u64 v[80:81], v[80:81], 3, s[10:11]
	v_mul_f32_e32 v82, v65, v67
	v_mul_f32_e32 v67, v64, v67
	v_fma_f32 v64, v64, v68, -v82
	v_fmac_f32_e32 v67, v65, v68
	v_cvt_pk_bf16_f32 v64, v64, s0
	v_cvt_pk_bf16_f32 v65, v67, s0
	global_store_short v[84:85], v64, off offset:256
	global_store_short v[84:85], v65, off offset:320
	v_mov_b32_e32 v64, v224
	v_mov_b32_e32 v65, v225
	v_ashrrev_i32_e32 v67, 31, v66
	v_lshl_add_u64 v[66:67], s[14:15], 0, v[66:67]
	v_mad_u64_u32 v[84:85], s[0:1], v66, s41, v[70:71]
	s_waitcnt lgkmcnt(0)
	v_mul_f32_e32 v68, v44, v76
	v_add_u32_e32 v80, s46, v121
	v_mul_f32_e32 v66, v60, v76
	v_mad_i32_i24 v85, v67, s41, v85
	v_lshl_or_b32 v82, v80, 5, v105
	v_ashrrev_i32_e32 v83, 31, v82
	v_lshl_add_u64 v[82:83], v[82:83], 3, s[10:11]
	v_ashrrev_i32_e32 v81, 31, v80
	v_lshl_add_u64 v[80:81], s[14:15], 0, v[80:81]
	v_mul_f32_e32 v67, v65, v68
	v_mul_f32_e32 v68, v64, v68
	v_fma_f32 v64, v64, v66, -v67
	v_fmac_f32_e32 v68, v65, v66
	v_cvt_pk_bf16_f32 v64, v64, s0
	v_cvt_pk_bf16_f32 v65, v68, s0
	global_store_short v[84:85], v64, off offset:256
	global_store_short v[84:85], v65, off offset:320
	v_mov_b32_e32 v64, v226
	v_mov_b32_e32 v65, v227
	v_mul_f32_e32 v68, v45, v77
	v_add_u32_e32 v66, s46, v122
	v_mul_f32_e32 v67, v61, v77
	v_lshl_or_b32 v82, v66, 5, v105
	v_mad_u64_u32 v[84:85], s[0:1], v80, s41, v[70:71]
	v_ashrrev_i32_e32 v83, 31, v82
	v_mad_i32_i24 v85, v81, s41, v85
	v_lshl_add_u64 v[82:83], v[82:83], 3, s[10:11]
	v_mul_f32_e32 v76, v65, v68
	v_mul_f32_e32 v68, v64, v68
	v_fma_f32 v64, v64, v67, -v76
	v_fmac_f32_e32 v68, v65, v67
	v_cvt_pk_bf16_f32 v64, v64, s0
	v_cvt_pk_bf16_f32 v65, v68, s0
	global_store_short v[84:85], v64, off offset:256
	global_store_short v[84:85], v65, off offset:320
	v_mov_b32_e32 v64, v228
	v_mov_b32_e32 v65, v229
	v_ashrrev_i32_e32 v67, 31, v66
	v_lshl_add_u64 v[66:67], s[14:15], 0, v[66:67]
	v_mad_u64_u32 v[82:83], s[0:1], v66, s41, v[70:71]
	v_mul_f32_e32 v68, v46, v78
	v_add_u32_e32 v76, s46, v123
	v_mul_f32_e32 v66, v62, v78
	v_mad_i32_i24 v83, v67, s41, v83
	v_lshl_or_b32 v80, v76, 5, v105
	v_ashrrev_i32_e32 v81, 31, v80
	v_lshl_add_u64 v[80:81], v[80:81], 3, s[10:11]
	v_ashrrev_i32_e32 v77, 31, v76
	v_mul_f32_e32 v67, v65, v68
	v_mul_f32_e32 v68, v64, v68
	v_fma_f32 v64, v64, v66, -v67
	v_fmac_f32_e32 v68, v65, v66
	v_cvt_pk_bf16_f32 v64, v64, s0
	v_cvt_pk_bf16_f32 v65, v68, s0
	global_store_short v[82:83], v64, off offset:256
	global_store_short v[82:83], v65, off offset:320
	v_mov_b32_e32 v64, v230
	v_mov_b32_e32 v65, v231
	v_lshl_add_u64 v[66:67], s[14:15], 0, v[76:77]
	v_mad_u64_u32 v[76:77], s[0:1], v66, s41, v[70:71]
	v_mul_f32_e32 v68, v47, v79
	v_mul_f32_e32 v66, v63, v79
	v_mad_i32_i24 v77, v67, s41, v77
	v_mul_f32_e32 v67, v65, v68
	v_mul_f32_e32 v68, v64, v68
	v_fma_f32 v64, v64, v66, -v67
	v_fmac_f32_e32 v68, v65, v66
	v_cvt_pk_bf16_f32 v64, v64, s0
	v_cvt_pk_bf16_f32 v65, v68, s0
	global_store_short v[76:77], v64, off offset:256
	global_store_short v[76:77], v65, off offset:320

; #define MFMA(a, b, c) __builtin_amdgcn_mfma_f32_32x32x16_bf16((a), (b), (c), 0, 0, 0)
; DI void gt_compute(const bf16* asr, const bf16* bsr, f32x16& acc0, f32x16& acc1, f32x16& acc2, f32x16& acc3) {
;   bf16x8 a[4], b0[4], b1[4], b2[4], b3[4];
; #pragma unroll
;   for (int kk = 0; kk < 4; ++kk) {
;     a[kk] = *(const bf16x8*)(asr + kk * 16);
;     b0[kk] = *(const bf16x8*)(bsr + kk * 16);
;     b1[kk] = *(const bf16x8*)(bsr + 32 * LDT + kk * 16);
;     b2[kk] = *(const bf16x8*)(bsr + 64 * LDT + kk * 16);
;     b3[kk] = *(const bf16x8*)(bsr + 96 * LDT + kk * 16);
;   }
;   __builtin_amdgcn_sched_barrier(0);
;   __builtin_amdgcn_s_setprio(2);
; #pragma unroll
;   for (int kk = 0; kk < 4; ++kk) {
;     acc0 = MFMA(a[kk], b0[kk], acc0); acc1 = MFMA(a[kk], b1[kk], acc1); acc2 = MFMA(a[kk], b2[kk], acc2); acc3 = MFMA(a[kk], b3[kk], acc3);
;   }
;   __builtin_amdgcn_s_setprio(0);
;   __builtin_amdgcn_sched_barrier(0);
; DI void gemm_mainloop(const bf16* __restrict__ A, int lda, const bf16* __restrict__ Bt, int ldb, int K, int m0, int n0,
;                       bf16* As, bf16* Bs, f32x16& acc0, f32x16& acc1, f32x16& acc2, f32x16& acc3) {
;     ...
;   for (int k0 = 0; k0 < K; k0 += 128) {
;     __syncthreads();
;     gt_store(t0, asw, bsw);
;     __syncthreads();
;     if (k0 + 128 < K) gt_load(t0, ap, bp, lda, ldb, KW(k0 + 128));
;     gt_compute(asr, bsr, acc0, acc1, acc2, acc3);
;     __syncthreads();
;     gt_store(t1, asw, bsw);
;     __syncthreads();
;     if (k0 + 192 < K) gt_load(t1, ap, bp, lda, ldb, KW(k0 + 192));
;     gt_compute(asr, bsr, acc0, acc1, acc2, acc3);
.Lmy_rss_kv:
	s_or_b64 exec, exec, s[98:99]
	s_waitcnt lgkmcnt(0)
	s_barrier
	s_waitcnt vmcnt(13)
	ds_write_b128 v64, v[8:11]
	ds_write_b128 v64, v[0:3] offset:4608
	ds_write_b128 v64, v[4:7] offset:9216
	s_waitcnt vmcnt(11)
	ds_write_b128 v64, v[16:19] offset:13824
	ds_write_b128 v64, v[12:15] offset:18432
	s_waitcnt vmcnt(10)
	ds_write_b128 v64, v[20:23] offset:23040
	s_waitcnt vmcnt(9)
	ds_write_b128 v64, v[24:27] offset:27648
	s_waitcnt vmcnt(8)
	ds_write_b128 v64, v[28:31] offset:32256
	v_lshl_add_u64 v[0:1], v[126:127], 0, s[48:49]
	v_add_co_u32_e32 v4, vcc, s38, v0
	s_waitcnt lgkmcnt(0)
	s_nop 0
	v_addc_co_u32_e32 v5, vcc, 0, v1, vcc
	v_add_co_u32_e32 v6, vcc, s39, v0
	s_barrier
	s_nop 0
	v_addc_co_u32_e32 v7, vcc, 0, v1, vcc
	global_load_dwordx4 v[142:145], v[4:5], off offset:256
	global_load_dwordx4 v[146:149], v[6:7], off offset:256
	v_add_co_u32_e32 v4, vcc, s40, v0
	v_lshl_add_u64 v[2:3], v[128:129], 0, s[48:49]
	s_nop 0
	v_addc_co_u32_e32 v5, vcc, 0, v1, vcc
	global_load_dwordx4 v[150:153], v[0:1], off offset:256
	global_load_dwordx4 v[154:157], v[2:3], off offset:256
	v_add_co_u32_e32 v0, vcc, s41, v2
	s_nop 1
	v_addc_co_u32_e32 v1, vcc, 0, v3, vcc
	global_load_dwordx4 v[162:165], v[4:5], off offset:256
	global_load_dwordx4 v[166:169], v[0:1], off offset:256
	v_add_co_u32_e32 v0, vcc, s42, v2
	s_nop 1
	v_addc_co_u32_e32 v1, vcc, 0, v3, vcc
	v_add_co_u32_e32 v2, vcc, s43, v2
	s_nop 1
	v_addc_co_u32_e32 v3, vcc, 0, v3, vcc
	global_load_dwordx4 v[170:173], v[0:1], off offset:256
	global_load_dwordx4 v[174:177], v[2:3], off offset:256
	v_and_b32_e32 v1, 31, v40
	v_lshrrev_b32_e32 v0, 1, v40
	v_and_or_b32 v2, v0, s45, v1
	v_and_b32_e32 v0, 16, v0
	v_mad_u64_u32 v[66:67], s[48:49], v2, s44, v[0:1]
	v_mad_u32_u24 v72, v1, s44, v0
	ds_read_b128 v[0:3], v66
	ds_read_b128 v[178:181], v66 offset:32
	ds_read_b128 v[4:7], v72 offset:18432
	ds_read_b128 v[182:185], v72 offset:18464
	ds_read_b128 v[8:11], v72 offset:23040
	ds_read_b128 v[186:189], v72 offset:23072
	ds_read_b128 v[12:15], v72 offset:27648
	ds_read_b128 v[190:193], v72 offset:27680
	ds_read_b128 v[194:197], v72 offset:32256
	ds_read_b128 v[198:201], v72 offset:32288
	ds_read_b128 v[202:205], v66 offset:64
	ds_read_b128 v[206:209], v66 offset:96
	ds_read_b128 v[210:213], v72 offset:18496
	ds_read_b128 v[214:217], v72 offset:18528
	ds_read_b128 v[218:221], v72 offset:23104
	ds_read_b128 v[222:225], v72 offset:23136
	ds_read_b128 v[226:229], v72 offset:27712
	ds_read_b128 v[230:233], v72 offset:27744
	ds_read_b128 v[234:237], v72 offset:32320
	ds_read_b128 v[238:241], v72 offset:32352
	s_waitcnt lgkmcnt(14)
	v_mfma_f32_32x32x16_bf16 v[48:63], v[0:3], v[4:7], 0
	v_mfma_f32_32x32x16_bf16 v[32:47], v[0:3], v[8:11], 0
	s_waitcnt lgkmcnt(13)
	v_mfma_f32_32x32x16_bf16 v[16:31], v[0:3], v[12:15], 0
	s_waitcnt lgkmcnt(11)
	v_mfma_f32_32x32x16_bf16 v[0:15], v[0:3], v[194:197], 0
	v_mfma_f32_32x32x16_bf16 v[48:63], v[178:181], v[182:185], v[48:63]
	v_mfma_f32_32x32x16_bf16 v[32:47], v[178:181], v[186:189], v[32:47]
	v_mfma_f32_32x32x16_bf16 v[16:31], v[178:181], v[190:193], v[16:31]
	s_waitcnt lgkmcnt(10)
	v_mfma_f32_32x32x16_bf16 v[0:15], v[178:181], v[198:201], v[0:15]
	s_waitcnt lgkmcnt(7)
	v_mfma_f32_32x32x16_bf16 v[48:63], v[202:205], v[210:213], v[48:63]
	s_waitcnt lgkmcnt(5)
	v_mfma_f32_32x32x16_bf16 v[32:47], v[202:205], v[218:221], v[32:47]
	s_waitcnt lgkmcnt(3)
	v_mfma_f32_32x32x16_bf16 v[16:31], v[202:205], v[226:229], v[16:31]
	s_waitcnt lgkmcnt(1)
	v_mfma_f32_32x32x16_bf16 v[0:15], v[202:205], v[234:237], v[0:15]
	v_mfma_f32_32x32x16_bf16 v[48:63], v[206:209], v[214:217], v[48:63]
	v_mfma_f32_32x32x16_bf16 v[32:47], v[206:209], v[222:225], v[32:47]
	v_mfma_f32_32x32x16_bf16 v[16:31], v[206:209], v[230:233], v[16:31]
	s_waitcnt lgkmcnt(0)
	v_mfma_f32_32x32x16_bf16 v[0:15], v[206:209], v[238:241], v[0:15]
	s_cmp_gt_i32 s18, 0
	s_cselect_b32 s19, -1, 0
	s_cselect_b32 s18, 0xfffffe00, 0
	s_barrier
	s_waitcnt vmcnt(13)
	ds_write_b128 v64, v[92:95]
	ds_write_b128 v64, v[68:71] offset:4608
	ds_write_b128 v64, v[88:91] offset:9216
	s_waitcnt vmcnt(11)
	ds_write_b128 v64, v[122:125] offset:13824
	ds_write_b128 v64, v[96:99] offset:18432
	s_waitcnt vmcnt(10)
	ds_write_b128 v64, v[130:133] offset:23040
	s_waitcnt vmcnt(9)
	ds_write_b128 v64, v[134:137] offset:27648
	s_waitcnt vmcnt(8)
	ds_write_b128 v64, v[138:141] offset:32256
	v_lshl_add_u64 v[92:93], v[126:127], 0, s[18:19]
	v_add_co_u32_e32 v68, vcc, s38, v92
	v_lshl_add_u64 v[126:127], v[128:129], 0, s[18:19]
	s_nop 0
	v_addc_co_u32_e32 v69, vcc, 0, v93, vcc
	v_add_co_u32_e32 v88, vcc, s39, v92
	s_waitcnt lgkmcnt(0)
	s_nop 0
	v_addc_co_u32_e32 v89, vcc, 0, v93, vcc
	v_add_co_u32_e32 v122, vcc, s40, v92
	s_barrier
; #define MFMA(a, b, c) __builtin_amdgcn_mfma_f32_32x32x16_bf16((a), (b), (c), 0, 0, 0)
; DI void gt_compute(const bf16* asr, const bf16* bsr, f32x16& acc0, f32x16& acc1, f32x16& acc2, f32x16& acc3) {
;   bf16x8 a[4], b0[4], b1[4], b2[4], b3[4];
; #pragma unroll
;   for (int kk = 0; kk < 4; ++kk) {
;     a[kk] = *(const bf16x8*)(asr + kk * 16);
;     b0[kk] = *(const bf16x8*)(bsr + kk * 16);
;     b1[kk] = *(const bf16x8*)(bsr + 32 * LDT + kk * 16);
;     b2[kk] = *(const bf16x8*)(bsr + 64 * LDT + kk * 16);
;     b3[kk] = *(const bf16x8*)(bsr + 96 * LDT + kk * 16);
;   }
;   __builtin_amdgcn_sched_barrier(0);
;   __builtin_amdgcn_s_setprio(2);
; #pragma unroll
;   for (int kk = 0; kk < 4; ++kk) {
;     acc0 = MFMA(a[kk], b0[kk], acc0); acc1 = MFMA(a[kk], b1[kk], acc1); acc2 = MFMA(a[kk], b2[kk], acc2); acc3 = MFMA(a[kk], b3[kk], acc3);
;   }
;   __builtin_amdgcn_s_setprio(0);
;   __builtin_amdgcn_sched_barrier(0);
; DI void gemm_mainloop(const bf16* __restrict__ A, int lda, const bf16* __restrict__ Bt, int ldb, int K, int m0, int n0,
;                       bf16* As, bf16* Bs, f32x16& acc0, f32x16& acc1, f32x16& acc2, f32x16& acc3) {
;     ...
;   for (int k0 = 0; k0 < K; k0 += 128) {
;     __syncthreads();
;     gt_store(t0, asw, bsw);
;     __syncthreads();
;     if (k0 + 128 < K) gt_load(t0, ap, bp, lda, ldb, KW(k0 + 128));
;     gt_compute(asr, bsr, acc0, acc1, acc2, acc3);
;     __syncthreads();
;     gt_store(t1, asw, bsw);
;     __syncthreads();
;     if (k0 + 192 < K) gt_load(t1, ap, bp, lda, ldb, KW(k0 + 192));
;     gt_compute(asr, bsr, acc0, acc1, acc2, acc3);
	s_nop 0
	v_addc_co_u32_e32 v123, vcc, 0, v93, vcc
	v_add_co_u32_e32 v128, vcc, s41, v126
	s_nop 1
	v_addc_co_u32_e32 v129, vcc, 0, v127, vcc
	global_load_dwordx4 v[68:71], v[68:69], off offset:384
	s_nop 0
	global_load_dwordx4 v[88:91], v[88:89], off offset:384
	s_nop 0
	global_load_dwordx4 v[92:95], v[92:93], off offset:384
	s_nop 0
	global_load_dwordx4 v[96:99], v[126:127], off offset:384
	s_nop 0
	global_load_dwordx4 v[122:125], v[122:123], off offset:384
	s_nop 0
	global_load_dwordx4 v[130:133], v[128:129], off offset:384
	v_add_co_u32_e32 v128, vcc, s42, v126
	s_nop 1
	v_addc_co_u32_e32 v129, vcc, 0, v127, vcc
	v_add_co_u32_e32 v126, vcc, s43, v126
	s_nop 1
	v_addc_co_u32_e32 v127, vcc, 0, v127, vcc
	global_load_dwordx4 v[134:137], v[128:129], off offset:384
	global_load_dwordx4 v[138:141], v[126:127], off offset:384
	ds_read_b128 v[178:181], v66
	ds_read_b128 v[182:185], v66 offset:32
	ds_read_b128 v[186:189], v72 offset:18432
	ds_read_b128 v[190:193], v72 offset:18464
	ds_read_b128 v[194:197], v72 offset:23040
	ds_read_b128 v[198:201], v72 offset:23072
	ds_read_b128 v[202:205], v72 offset:27648
	ds_read_b128 v[206:209], v72 offset:27680
	ds_read_b128 v[210:213], v72 offset:32256
	ds_read_b128 v[214:217], v72 offset:32288
	ds_read_b128 v[218:221], v66 offset:64
	ds_read_b128 v[222:225], v66 offset:96
	ds_read_b128 v[226:229], v72 offset:18496
	ds_read_b128 v[230:233], v72 offset:18528
	ds_read_b128 v[234:237], v72 offset:23104
	ds_read_b128 v[238:241], v72 offset:23136
	ds_read_b128 v[242:245], v72 offset:27712
	ds_read_b128 v[246:249], v72 offset:27744
	ds_read_b128 v[250:253], v72 offset:32320
	ds_read_b128 v[126:129], v72 offset:32352
	s_waitcnt lgkmcnt(14)
	v_mfma_f32_32x32x16_bf16 v[48:63], v[178:181], v[186:189], v[48:63]
	v_mfma_f32_32x32x16_bf16 v[32:47], v[178:181], v[194:197], v[32:47]
	s_waitcnt lgkmcnt(13)
	v_mfma_f32_32x32x16_bf16 v[16:31], v[178:181], v[202:205], v[16:31]
	s_waitcnt lgkmcnt(11)
	v_mfma_f32_32x32x16_bf16 v[0:15], v[178:181], v[210:213], v[0:15]
	v_mfma_f32_32x32x16_bf16 v[48:63], v[182:185], v[190:193], v[48:63]
	v_mfma_f32_32x32x16_bf16 v[32:47], v[182:185], v[198:201], v[32:47]
	v_mfma_f32_32x32x16_bf16 v[16:31], v[182:185], v[206:209], v[16:31]
	s_waitcnt lgkmcnt(10)
	v_mfma_f32_32x32x16_bf16 v[0:15], v[182:185], v[214:217], v[0:15]
	s_waitcnt lgkmcnt(7)
	v_mfma_f32_32x32x16_bf16 v[48:63], v[218:221], v[226:229], v[48:63]
	s_waitcnt lgkmcnt(5)
	v_mfma_f32_32x32x16_bf16 v[32:47], v[218:221], v[234:237], v[32:47]
	s_waitcnt lgkmcnt(3)
	v_mfma_f32_32x32x16_bf16 v[16:31], v[218:221], v[242:245], v[16:31]
	s_waitcnt lgkmcnt(1)
	v_mfma_f32_32x32x16_bf16 v[0:15], v[218:221], v[250:253], v[0:15]
	v_mfma_f32_32x32x16_bf16 v[48:63], v[222:225], v[230:233], v[48:63]
	v_mfma_f32_32x32x16_bf16 v[32:47], v[222:225], v[238:241], v[32:47]
	v_mfma_f32_32x32x16_bf16 v[16:31], v[222:225], v[246:249], v[16:31]
	s_waitcnt lgkmcnt(0)
	v_mfma_f32_32x32x16_bf16 v[0:15], v[222:225], v[126:129], v[0:15]
	s_barrier
	s_waitcnt vmcnt(13)
	ds_write_b128 v64, v[150:153]
	ds_write_b128 v64, v[142:145] offset:4608
	ds_write_b128 v64, v[146:149] offset:9216
	s_waitcnt vmcnt(11)
	ds_write_b128 v64, v[162:165] offset:13824
	ds_write_b128 v64, v[154:157] offset:18432
	s_waitcnt vmcnt(10)
	ds_write_b128 v64, v[166:169] offset:23040
	s_waitcnt vmcnt(9)
	ds_write_b128 v64, v[170:173] offset:27648
	s_waitcnt vmcnt(8)
	ds_write_b128 v64, v[174:177] offset:32256
	s_waitcnt lgkmcnt(0)
	s_barrier
	ds_read_b128 v[126:129], v66
	ds_read_b128 v[142:145], v66 offset:32
	ds_read_b128 v[146:149], v72 offset:18432
	ds_read_b128 v[150:153], v72 offset:18464
	ds_read_b128 v[154:157], v72 offset:23040
	ds_read_b128 v[162:165], v72 offset:23072
	ds_read_b128 v[166:169], v72 offset:27648
	ds_read_b128 v[170:173], v72 offset:27680
	ds_read_b128 v[174:177], v72 offset:32256
	ds_read_b128 v[178:181], v72 offset:32288
	ds_read_b128 v[182:185], v66 offset:64
	ds_read_b128 v[186:189], v66 offset:96
	ds_read_b128 v[190:193], v72 offset:18496
	ds_read_b128 v[194:197], v72 offset:18528
	ds_read_b128 v[198:201], v72 offset:23104
	ds_read_b128 v[202:205], v72 offset:23136
	ds_read_b128 v[206:209], v72 offset:27712
	ds_read_b128 v[210:213], v72 offset:27744
	ds_read_b128 v[214:217], v72 offset:32320
	ds_read_b128 v[218:221], v72 offset:32352
	s_waitcnt lgkmcnt(14)
	v_mfma_f32_32x32x16_bf16 v[48:63], v[126:129], v[146:149], v[48:63]
	v_mfma_f32_32x32x16_bf16 v[32:47], v[126:129], v[154:157], v[32:47]
	s_waitcnt lgkmcnt(13)
	v_mfma_f32_32x32x16_bf16 v[16:31], v[126:129], v[166:169], v[16:31]
	s_waitcnt lgkmcnt(11)
	v_mfma_f32_32x32x16_bf16 v[0:15], v[126:129], v[174:177], v[0:15]
	v_mfma_f32_32x32x16_bf16 v[48:63], v[142:145], v[150:153], v[48:63]
	v_mfma_f32_32x32x16_bf16 v[32:47], v[142:145], v[162:165], v[32:47]
	v_mfma_f32_32x32x16_bf16 v[16:31], v[142:145], v[170:173], v[16:31]
	s_waitcnt lgkmcnt(10)
	v_mfma_f32_32x32x16_bf16 v[0:15], v[142:145], v[178:181], v[0:15]
	s_waitcnt lgkmcnt(7)
	v_mfma_f32_32x32x16_bf16 v[48:63], v[182:185], v[190:193], v[48:63]
	s_waitcnt lgkmcnt(5)
	v_mfma_f32_32x32x16_bf16 v[32:47], v[182:185], v[198:201], v[32:47]
	s_waitcnt lgkmcnt(3)
	v_mfma_f32_32x32x16_bf16 v[16:31], v[182:185], v[206:209], v[16:31]
	s_waitcnt lgkmcnt(1)
	v_mfma_f32_32x32x16_bf16 v[0:15], v[182:185], v[214:217], v[0:15]
	v_mfma_f32_32x32x16_bf16 v[48:63], v[186:189], v[194:197], v[48:63]
	v_mfma_f32_32x32x16_bf16 v[32:47], v[186:189], v[202:205], v[32:47]
	v_mfma_f32_32x32x16_bf16 v[16:31], v[186:189], v[210:213], v[16:31]
	s_waitcnt lgkmcnt(0)
	v_mfma_f32_32x32x16_bf16 v[0:15], v[186:189], v[218:221], v[0:15]
	s_barrier
; DI void gemm_mainloop(const bf16* __restrict__ A, int lda, const bf16* __restrict__ Bt, int ldb, int K, int m0, int n0,
;                       bf16* As, bf16* Bs, f32x16& acc0, f32x16& acc1, f32x16& acc2, f32x16& acc3) {
;     ...
;   for (int k0 = 0; k0 < K; k0 += 128) {
;     __syncthreads();
;     gt_store(t0, asw, bsw);
;     __syncthreads();
;     if (k0 + 128 < K) gt_load(t0, ap, bp, lda, ldb, KW(k0 + 128));
;     gt_compute(asr, bsr, acc0, acc1, acc2, acc3);
;     __syncthreads();
;     gt_store(t1, asw, bsw);
;     __syncthreads();
;     if (k0 + 192 < K) gt_load(t1, ap, bp, lda, ldb, KW(k0 + 192));
;     gt_compute(asr, bsr, acc0, acc1, acc2, acc3);
;     ...
;       const int hh = nt >> 1;
;       if ((nt & 1) == 0) {
	s_waitcnt vmcnt(5)
	ds_write_b128 v64, v[92:95]
	ds_write_b128 v64, v[68:71] offset:4608
	ds_write_b128 v64, v[88:91] offset:9216
	s_waitcnt vmcnt(3)
	ds_write_b128 v64, v[122:125] offset:13824
	ds_write_b128 v64, v[96:99] offset:18432
	s_waitcnt vmcnt(2)
	ds_write_b128 v64, v[130:133] offset:23040
	s_waitcnt vmcnt(1)
	ds_write_b128 v64, v[134:137] offset:27648
	s_waitcnt vmcnt(0)
	ds_write_b128 v64, v[138:141] offset:32256
	s_waitcnt lgkmcnt(0)
	s_barrier
	ds_read_b128 v[68:71], v66
	ds_read_b128 v[88:91], v66 offset:32
	ds_read_b128 v[92:95], v72 offset:18432
	ds_read_b128 v[96:99], v72 offset:18464
	ds_read_b128 v[122:125], v72 offset:23040
	ds_read_b128 v[126:129], v72 offset:23072
	ds_read_b128 v[130:133], v72 offset:27648
	ds_read_b128 v[134:137], v72 offset:27680
	ds_read_b128 v[138:141], v72 offset:32256
	ds_read_b128 v[142:145], v72 offset:32288
	ds_read_b128 v[146:149], v66 offset:64
	ds_read_b128 v[64:67], v66 offset:96
	ds_read_b128 v[150:153], v72 offset:18496
	ds_read_b128 v[154:157], v72 offset:18528
	ds_read_b128 v[162:165], v72 offset:23104
	ds_read_b128 v[166:169], v72 offset:23136
	ds_read_b128 v[170:173], v72 offset:27712
	ds_read_b128 v[174:177], v72 offset:27744
	ds_read_b128 v[178:181], v72 offset:32320
	ds_read_b128 v[182:185], v72 offset:32352
	s_waitcnt lgkmcnt(14)
	v_mfma_f32_32x32x16_bf16 v[48:63], v[68:71], v[92:95], v[48:63]
	v_mfma_f32_32x32x16_bf16 v[32:47], v[68:71], v[122:125], v[32:47]
	s_waitcnt lgkmcnt(13)
	v_mfma_f32_32x32x16_bf16 v[16:31], v[68:71], v[130:133], v[16:31]
	s_waitcnt lgkmcnt(11)
	v_mfma_f32_32x32x16_bf16 v[0:15], v[68:71], v[138:141], v[0:15]
	v_mfma_f32_32x32x16_bf16 v[48:63], v[88:91], v[96:99], v[48:63]
	v_mfma_f32_32x32x16_bf16 v[32:47], v[88:91], v[126:129], v[32:47]
	v_mfma_f32_32x32x16_bf16 v[16:31], v[88:91], v[134:137], v[16:31]
	s_waitcnt lgkmcnt(10)
	v_mfma_f32_32x32x16_bf16 v[0:15], v[88:91], v[142:145], v[0:15]
	s_waitcnt lgkmcnt(7)
	v_mfma_f32_32x32x16_bf16 v[48:63], v[146:149], v[150:153], v[48:63]
	s_waitcnt lgkmcnt(5)
	v_mfma_f32_32x32x16_bf16 v[32:47], v[146:149], v[162:165], v[32:47]
	s_waitcnt lgkmcnt(3)
	v_mfma_f32_32x32x16_bf16 v[16:31], v[146:149], v[170:173], v[16:31]
	s_waitcnt lgkmcnt(1)
	v_mfma_f32_32x32x16_bf16 v[0:15], v[146:149], v[178:181], v[0:15]
	v_mfma_f32_32x32x16_bf16 v[48:63], v[64:67], v[154:157], v[48:63]
	v_mfma_f32_32x32x16_bf16 v[32:47], v[64:67], v[166:169], v[32:47]
	v_mfma_f32_32x32x16_bf16 v[16:31], v[64:67], v[174:177], v[16:31]
	s_waitcnt lgkmcnt(0)
	v_mfma_f32_32x32x16_bf16 v[0:15], v[64:67], v[182:185], v[0:15]
	s_and_b32 s0, s0, 0x780
	s_ashr_i32 s18, s1, 1
	s_bitcmp1_b32 s1, 0
	s_cselect_b64 s[48:49], -1, 0
	s_ashr_i32 s1, s28, 1
	s_and_b32 s1, s1, -8
	s_add_i32 s18, s1, s18
	s_ashr_i32 s19, s18, 31
	s_mov_b64 s[28:29], -1
	s_and_b64 vcc, exec, s[48:49]
	s_barrier
	s_cbranch_vccz .LBB0_348
;     ...
;         bf16* Vt = (bf16*)(ws + OFF_VT);
; #pragma unroll
;         for (int j = 0; j < 4; ++j)
; #pragma unroll
;           for (int qd = 0; qd < 4; ++qd) {
;             int rl = 32 * w + 8 * qd + 4 * g;
;             int s = (m0 & 2047) + rl;
;             uint2 o;
;             o.x = pack2(acc[j][4 * qd] * rs[rl], acc[j][4 * qd + 1] * rs[rl + 1]);
;             o.y = pack2(acc[j][4 * qd + 2] * rs[rl + 2], acc[j][4 * qd + 3] * rs[rl + 3]);
;             *(uint2*)(Vt + (((size_t)(bidx * 8 + hh) * 32 + (s >> 6)) * 128 + 32 * j + r) * 64 + (s & 63)) = o;
;           }
	ds_read_b128 v[64:67], v104 offset:40960
	ds_read_b128 v[68:71], v104 offset:40992
	v_add_u32_e32 v72, s0, v102
	s_lshl_b64 s[28:29], s[18:19], 19
	v_mov_b32_e32 v81, v73
	s_waitcnt lgkmcnt(1)
	v_pk_mul_f32 v[88:89], v[48:49], v[64:65]
	v_pk_mul_f32 v[90:91], v[50:51], v[66:67]
	v_cvt_pk_bf16_f32 v88, v88, v89
	v_cvt_pk_bf16_f32 v89, v90, v91
	v_ashrrev_i32_e32 v90, 6, v72
	v_ashrrev_i32_e32 v91, 31, v90
	v_lshlrev_b64 v[90:91], 14, v[90:91]
	v_lshl_add_u64 v[90:91], s[10:11], 0, v[90:91]
	v_lshl_add_u64 v[90:91], v[90:91], 0, s[28:29]
	v_lshl_add_u64 v[96:97], v[90:91], 0, v[76:77]
	v_lshl_add_u64 v[90:91], v[96:97], 0, v[80:81]
	global_store_dwordx2 v[90:91], v[88:89], off
	s_waitcnt lgkmcnt(0)
	v_pk_mul_f32 v[88:89], v[52:53], v[68:69]
	v_mov_b32_e32 v83, v73
	v_cvt_pk_bf16_f32 v92, v88, v89
	v_pk_mul_f32 v[88:89], v[54:55], v[70:71]
	v_lshl_add_u64 v[94:95], v[96:97], 0, v[82:83]
	v_cvt_pk_bf16_f32 v93, v88, v89
	ds_read_b128 v[88:91], v104 offset:41024
	global_store_dwordx2 v[94:95], v[92:93], off
	ds_read_b128 v[92:95], v104 offset:41056
	v_mov_b32_e32 v85, v73
	v_mov_b32_e32 v87, v73
	s_waitcnt lgkmcnt(1)
	v_pk_mul_f32 v[98:99], v[56:57], v[88:89]
	v_pk_mul_f32 v[122:123], v[58:59], v[90:91]
	v_cvt_pk_bf16_f32 v98, v98, v99
	v_cvt_pk_bf16_f32 v99, v122, v123
	v_lshl_add_u64 v[122:123], v[96:97], 0, v[84:85]
	global_store_dwordx2 v[122:123], v[98:99], off
	s_waitcnt lgkmcnt(0)
	v_pk_mul_f32 v[98:99], v[60:61], v[92:93]
	v_pk_mul_f32 v[122:123], v[62:63], v[94:95]
	v_cvt_pk_bf16_f32 v98, v98, v99
	v_cvt_pk_bf16_f32 v99, v122, v123
	v_lshl_add_u64 v[122:123], v[96:97], 0, v[86:87]
	global_store_dwordx2 v[122:123], v[98:99], off
	v_pk_mul_f32 v[98:99], v[32:33], v[64:65]
	v_pk_mul_f32 v[122:123], v[34:35], v[66:67]
	v_cvt_pk_bf16_f32 v98, v98, v99
	v_cvt_pk_bf16_f32 v99, v122, v123
	v_lshl_add_u64 v[122:123], v[96:97], 0, s[12:13]
	v_lshl_add_u64 v[124:125], v[122:123], 0, v[80:81]
	global_store_dwordx2 v[124:125], v[98:99], off
	v_pk_mul_f32 v[98:99], v[36:37], v[68:69]
	v_pk_mul_f32 v[124:125], v[38:39], v[70:71]
	v_cvt_pk_bf16_f32 v98, v98, v99
	v_cvt_pk_bf16_f32 v99, v124, v125
	v_lshl_add_u64 v[124:125], v[122:123], 0, v[82:83]
	global_store_dwordx2 v[124:125], v[98:99], off
	v_pk_mul_f32 v[98:99], v[40:41], v[88:89]
	v_pk_mul_f32 v[124:125], v[42:43], v[90:91]
	v_cvt_pk_bf16_f32 v98, v98, v99
	v_cvt_pk_bf16_f32 v99, v124, v125
	v_lshl_add_u64 v[124:125], v[122:123], 0, v[84:85]
	global_store_dwordx2 v[124:125], v[98:99], off
	v_pk_mul_f32 v[98:99], v[44:45], v[92:93]
	v_pk_mul_f32 v[124:125], v[46:47], v[94:95]
	v_cvt_pk_bf16_f32 v98, v98, v99
	v_cvt_pk_bf16_f32 v99, v124, v125
	v_lshl_add_u64 v[122:123], v[122:123], 0, v[86:87]
	global_store_dwordx2 v[122:123], v[98:99], off
	v_pk_mul_f32 v[98:99], v[16:17], v[64:65]
	v_pk_mul_f32 v[122:123], v[18:19], v[66:67]
	v_pk_mul_f32 v[64:65], v[0:1], v[64:65]
	v_pk_mul_f32 v[66:67], v[2:3], v[66:67]
	v_cvt_pk_bf16_f32 v98, v98, v99
	v_cvt_pk_bf16_f32 v99, v122, v123
	v_lshl_add_u64 v[122:123], v[96:97], 0, s[14:15]
	v_cvt_pk_bf16_f32 v64, v64, v65
	v_cvt_pk_bf16_f32 v65, v66, v67
	v_lshl_add_u64 v[66:67], v[96:97], 0, s[16:17]
	v_lshl_add_u64 v[124:125], v[122:123], 0, v[80:81]
	v_lshl_add_u64 v[96:97], v[66:67], 0, v[80:81]
	global_store_dwordx2 v[124:125], v[98:99], off
	v_pk_mul_f32 v[98:99], v[20:21], v[68:69]
	v_pk_mul_f32 v[124:125], v[22:23], v[70:71]
	global_store_dwordx2 v[96:97], v[64:65], off
	v_pk_mul_f32 v[64:65], v[4:5], v[68:69]
	v_pk_mul_f32 v[68:69], v[6:7], v[70:71]
	v_cvt_pk_bf16_f32 v98, v98, v99
	v_cvt_pk_bf16_f32 v99, v124, v125
	v_lshl_add_u64 v[124:125], v[122:123], 0, v[82:83]
	v_cvt_pk_bf16_f32 v64, v64, v65
	v_cvt_pk_bf16_f32 v65, v68, v69
	v_lshl_add_u64 v[68:69], v[66:67], 0, v[82:83]
	global_store_dwordx2 v[124:125], v[98:99], off
	v_pk_mul_f32 v[98:99], v[24:25], v[88:89]
	v_pk_mul_f32 v[124:125], v[26:27], v[90:91]
	global_store_dwordx2 v[68:69], v[64:65], off
	v_pk_mul_f32 v[64:65], v[8:9], v[88:89]
	v_pk_mul_f32 v[68:69], v[10:11], v[90:91]
	v_cvt_pk_bf16_f32 v98, v98, v99
	v_cvt_pk_bf16_f32 v99, v124, v125
	v_lshl_add_u64 v[124:125], v[122:123], 0, v[84:85]
	v_cvt_pk_bf16_f32 v64, v64, v65
	v_cvt_pk_bf16_f32 v65, v68, v69
	v_lshl_add_u64 v[68:69], v[66:67], 0, v[84:85]
	global_store_dwordx2 v[124:125], v[98:99], off
	v_pk_mul_f32 v[98:99], v[28:29], v[92:93]
	v_pk_mul_f32 v[124:125], v[30:31], v[94:95]
	global_store_dwordx2 v[68:69], v[64:65], off
	v_pk_mul_f32 v[64:65], v[12:13], v[92:93]
	v_pk_mul_f32 v[68:69], v[14:15], v[94:95]
	v_cvt_pk_bf16_f32 v98, v98, v99
	v_cvt_pk_bf16_f32 v99, v124, v125
	v_lshl_add_u64 v[122:123], v[122:123], 0, v[86:87]
	v_cvt_pk_bf16_f32 v64, v64, v65
	v_cvt_pk_bf16_f32 v65, v68, v69
	v_lshl_add_u64 v[66:67], v[66:67], 0, v[86:87]
	global_store_dwordx2 v[122:123], v[98:99], off
	global_store_dwordx2 v[66:67], v[64:65], off
	s_mov_b64 s[28:29], 0

; #define MFMA(a, b, c) __builtin_amdgcn_mfma_f32_32x32x16_bf16((a), (b), (c), 0, 0, 0)
; DI void gt_compute(const bf16* asr, const bf16* bsr, f32x16& acc0, f32x16& acc1, f32x16& acc2, f32x16& acc3) {
;   bf16x8 a[4], b0[4], b1[4], b2[4], b3[4];
; #pragma unroll
;   for (int kk = 0; kk < 4; ++kk) {
;     a[kk] = *(const bf16x8*)(asr + kk * 16);
;     b0[kk] = *(const bf16x8*)(bsr + kk * 16);
;     b1[kk] = *(const bf16x8*)(bsr + 32 * LDT + kk * 16);
;     b2[kk] = *(const bf16x8*)(bsr + 64 * LDT + kk * 16);
;     b3[kk] = *(const bf16x8*)(bsr + 96 * LDT + kk * 16);
;   }
;   __builtin_amdgcn_sched_barrier(0);
;   __builtin_amdgcn_s_setprio(2);
; #pragma unroll
;   for (int kk = 0; kk < 4; ++kk) {
;     acc0 = MFMA(a[kk], b0[kk], acc0); acc1 = MFMA(a[kk], b1[kk], acc1); acc2 = MFMA(a[kk], b2[kk], acc2); acc3 = MFMA(a[kk], b3[kk], acc3);
;   }
;   __builtin_amdgcn_s_setprio(0);
;   __builtin_amdgcn_sched_barrier(0);
; DI void gemm_mainloop(const bf16* __restrict__ A, int lda, const bf16* __restrict__ Bt, int ldb, int K, int m0, int n0,
;                       bf16* As, bf16* Bs, f32x16& acc0, f32x16& acc1, f32x16& acc2, f32x16& acc3) {
;     ...
;   for (int k0 = 0; k0 < K; k0 += 128) {
;     __syncthreads();
;     gt_store(t0, asw, bsw);
;     __syncthreads();
;     if (k0 + 128 < K) gt_load(t0, ap, bp, lda, ldb, KW(k0 + 128));
;     gt_compute(asr, bsr, acc0, acc1, acc2, acc3);
;     __syncthreads();
;     gt_store(t1, asw, bsw);
;     __syncthreads();
;     if (k0 + 192 < K) gt_load(t1, ap, bp, lda, ldb, KW(k0 + 192));
;     gt_compute(asr, bsr, acc0, acc1, acc2, acc3);
.LBB0_480:
	ds_read_b128 v[142:145], v138
	ds_read_b128 v[146:149], v138 offset:32
	ds_read_b128 v[150:153], v128 offset:18432
	ds_read_b128 v[154:157], v128 offset:18464
	ds_read_b128 v[166:169], v128 offset:23040
	ds_read_b128 v[170:173], v128 offset:23072
	ds_read_b128 v[174:177], v128 offset:27648
	ds_read_b128 v[178:181], v128 offset:27680
	ds_read_b128 v[182:185], v128 offset:32256
	ds_read_b128 v[186:189], v128 offset:32288
	ds_read_b128 v[190:193], v138 offset:64
	ds_read_b128 v[194:197], v138 offset:96
	ds_read_b128 v[198:201], v128 offset:18496
	ds_read_b128 v[202:205], v128 offset:18528
	ds_read_b128 v[206:209], v128 offset:23104
	ds_read_b128 v[210:213], v128 offset:23136
	ds_read_b128 v[214:217], v128 offset:27712
	ds_read_b128 v[228:231], v128 offset:27744
	ds_read_b128 v[232:235], v128 offset:32320
	ds_read_b128 v[236:239], v128 offset:32352
	s_waitcnt lgkmcnt(14)
	v_mfma_f32_32x32x16_bf16 v[48:63], v[142:145], v[150:153], v[48:63]
	v_mfma_f32_32x32x16_bf16 v[32:47], v[142:145], v[166:169], v[32:47]
	s_waitcnt lgkmcnt(13)
	v_mfma_f32_32x32x16_bf16 v[16:31], v[142:145], v[174:177], v[16:31]
	s_waitcnt lgkmcnt(11)
	v_mfma_f32_32x32x16_bf16 v[0:15], v[142:145], v[182:185], v[0:15]
	v_mfma_f32_32x32x16_bf16 v[48:63], v[146:149], v[154:157], v[48:63]
	v_mfma_f32_32x32x16_bf16 v[32:47], v[146:149], v[170:173], v[32:47]
	v_mfma_f32_32x32x16_bf16 v[16:31], v[146:149], v[178:181], v[16:31]
	s_waitcnt lgkmcnt(10)
	v_mfma_f32_32x32x16_bf16 v[0:15], v[146:149], v[186:189], v[0:15]
	s_waitcnt lgkmcnt(7)
	v_mfma_f32_32x32x16_bf16 v[48:63], v[190:193], v[198:201], v[48:63]
	s_waitcnt lgkmcnt(5)
	v_mfma_f32_32x32x16_bf16 v[32:47], v[190:193], v[206:209], v[32:47]
	s_waitcnt lgkmcnt(3)
	v_mfma_f32_32x32x16_bf16 v[16:31], v[190:193], v[214:217], v[16:31]
	s_waitcnt lgkmcnt(1)
	v_mfma_f32_32x32x16_bf16 v[0:15], v[190:193], v[232:235], v[0:15]
	v_mfma_f32_32x32x16_bf16 v[48:63], v[194:197], v[202:205], v[48:63]
	v_mfma_f32_32x32x16_bf16 v[32:47], v[194:197], v[210:213], v[32:47]
	v_mfma_f32_32x32x16_bf16 v[16:31], v[194:197], v[228:231], v[16:31]
	s_waitcnt lgkmcnt(0)
	v_mfma_f32_32x32x16_bf16 v[0:15], v[194:197], v[236:239], v[0:15]
	s_add_i32 s6, s34, 0xffffff80
	s_cmpk_lt_u32 s6, 0x380
	s_mov_b64 s[30:31], s[34:35]
	s_cbranch_scc0 .LBB0_478

; #define MFMA(a, b, c) __builtin_amdgcn_mfma_f32_32x32x16_bf16((a), (b), (c), 0, 0, 0)
; DI void gt_compute(const bf16* asr, const bf16* bsr, f32x16& acc0, f32x16& acc1, f32x16& acc2, f32x16& acc3) {
;   bf16x8 a[4], b0[4], b1[4], b2[4], b3[4];
; #pragma unroll
;   for (int kk = 0; kk < 4; ++kk) {
;     a[kk] = *(const bf16x8*)(asr + kk * 16);
;     b0[kk] = *(const bf16x8*)(bsr + kk * 16);
;     b1[kk] = *(const bf16x8*)(bsr + 32 * LDT + kk * 16);
;     b2[kk] = *(const bf16x8*)(bsr + 64 * LDT + kk * 16);
;     b3[kk] = *(const bf16x8*)(bsr + 96 * LDT + kk * 16);
;   }
;   __builtin_amdgcn_sched_barrier(0);
;   __builtin_amdgcn_s_setprio(2);
; #pragma unroll
;   for (int kk = 0; kk < 4; ++kk) {
;     acc0 = MFMA(a[kk], b0[kk], acc0); acc1 = MFMA(a[kk], b1[kk], acc1); acc2 = MFMA(a[kk], b2[kk], acc2); acc3 = MFMA(a[kk], b3[kk], acc3);
;   }
;   __builtin_amdgcn_s_setprio(0);
;   __builtin_amdgcn_sched_barrier(0);
; DI void gemm_mainloop(const bf16* __restrict__ A, int lda, const bf16* __restrict__ Bt, int ldb, int K, int m0, int n0,
;                       bf16* As, bf16* Bs, f32x16& acc0, f32x16& acc1, f32x16& acc2, f32x16& acc3) {
;     ...
;   for (int k0 = 0; k0 < K; k0 += 128) {
;     __syncthreads();
;     gt_store(t0, asw, bsw);
;     __syncthreads();
;     if (k0 + 128 < K) gt_load(t0, ap, bp, lda, ldb, KW(k0 + 128));
;     gt_compute(asr, bsr, acc0, acc1, acc2, acc3);
;     __syncthreads();
;     gt_store(t1, asw, bsw);
;     __syncthreads();
;     if (k0 + 192 < K) gt_load(t1, ap, bp, lda, ldb, KW(k0 + 192));
;     gt_compute(asr, bsr, acc0, acc1, acc2, acc3);
.LBB0_483:
	ds_read_b128 v[142:145], v138
	ds_read_b128 v[146:149], v138 offset:32
	ds_read_b128 v[150:153], v128 offset:18432
	ds_read_b128 v[154:157], v128 offset:18464
	ds_read_b128 v[166:169], v128 offset:23040
	ds_read_b128 v[170:173], v128 offset:23072
	ds_read_b128 v[174:177], v128 offset:27648
	ds_read_b128 v[178:181], v128 offset:27680
	ds_read_b128 v[182:185], v128 offset:32256
	ds_read_b128 v[186:189], v128 offset:32288
	ds_read_b128 v[190:193], v138 offset:64
	ds_read_b128 v[194:197], v138 offset:96
	ds_read_b128 v[198:201], v128 offset:18496
	ds_read_b128 v[202:205], v128 offset:18528
	ds_read_b128 v[206:209], v128 offset:23104
	ds_read_b128 v[210:213], v128 offset:23136
	ds_read_b128 v[214:217], v128 offset:27712
	ds_read_b128 v[228:231], v128 offset:27744
	ds_read_b128 v[232:235], v128 offset:32320
	ds_read_b128 v[236:239], v128 offset:32352
	s_waitcnt lgkmcnt(14)
	v_mfma_f32_32x32x16_bf16 v[48:63], v[142:145], v[150:153], v[48:63]
	v_mfma_f32_32x32x16_bf16 v[32:47], v[142:145], v[166:169], v[32:47]
	s_waitcnt lgkmcnt(13)
	v_mfma_f32_32x32x16_bf16 v[16:31], v[142:145], v[174:177], v[16:31]
	s_waitcnt lgkmcnt(11)
	v_mfma_f32_32x32x16_bf16 v[0:15], v[142:145], v[182:185], v[0:15]
	v_mfma_f32_32x32x16_bf16 v[48:63], v[146:149], v[154:157], v[48:63]
	v_mfma_f32_32x32x16_bf16 v[32:47], v[146:149], v[170:173], v[32:47]
	v_mfma_f32_32x32x16_bf16 v[16:31], v[146:149], v[178:181], v[16:31]
	s_waitcnt lgkmcnt(10)
	v_mfma_f32_32x32x16_bf16 v[0:15], v[146:149], v[186:189], v[0:15]
	s_waitcnt lgkmcnt(7)
	v_mfma_f32_32x32x16_bf16 v[48:63], v[190:193], v[198:201], v[48:63]
	s_waitcnt lgkmcnt(5)
	v_mfma_f32_32x32x16_bf16 v[32:47], v[190:193], v[206:209], v[32:47]
	s_waitcnt lgkmcnt(3)
	v_mfma_f32_32x32x16_bf16 v[16:31], v[190:193], v[214:217], v[16:31]
	s_waitcnt lgkmcnt(1)
	v_mfma_f32_32x32x16_bf16 v[0:15], v[190:193], v[232:235], v[0:15]
	v_mfma_f32_32x32x16_bf16 v[48:63], v[194:197], v[202:205], v[48:63]
	v_mfma_f32_32x32x16_bf16 v[32:47], v[194:197], v[210:213], v[32:47]
	v_mfma_f32_32x32x16_bf16 v[16:31], v[194:197], v[228:231], v[16:31]
	s_waitcnt lgkmcnt(0)
	v_mfma_f32_32x32x16_bf16 v[0:15], v[194:197], v[236:239], v[0:15]
	s_cmpk_gt_u32 s30, 0x33f
	s_barrier
	s_waitcnt vmcnt(5)
	ds_write_b128 v136, v[100:103]
	ds_write_b128 v136, v[88:91] offset:4608
	ds_write_b128 v136, v[92:95] offset:9216
	s_waitcnt vmcnt(3)
	ds_write_b128 v136, v[112:115] offset:13824
	ds_write_b128 v136, v[108:111] offset:18432
	s_waitcnt vmcnt(2)
	ds_write_b128 v136, v[116:119] offset:23040
	s_waitcnt vmcnt(1)
	ds_write_b128 v136, v[120:123] offset:27648
	s_waitcnt vmcnt(0)
	ds_write_b128 v136, v[124:127] offset:32256
	s_waitcnt lgkmcnt(0)
	s_barrier
	s_cbranch_scc1 .LBB0_480
	s_cmp_lt_i32 s30, s45
	s_cselect_b32 s7, 0, -1
	s_cselect_b32 s6, 0, 0xfffffc00
	s_add_u32 s30, s28, s30
	s_addc_u32 s31, s29, s31
	s_add_u32 s6, s30, s6
	s_addc_u32 s7, s31, s7
	s_lshl_b64 s[6:7], s[6:7], 1
	v_lshl_add_u64 v[100:101], v[132:133], 0, s[6:7]
	v_add_co_u32_e32 v88, vcc, s4, v100
	v_lshl_add_u64 v[120:121], v[134:135], 0, s[6:7]
	s_nop 0
	v_addc_co_u32_e32 v89, vcc, 0, v101, vcc
	v_add_co_u32_e32 v92, vcc, 0x20000, v100
	s_nop 1
	v_addc_co_u32_e32 v93, vcc, 0, v101, vcc
	v_add_co_u32_e32 v112, vcc, 0x30000, v100
	global_load_dwordx4 v[88:91], v[88:89], off offset:384
	s_nop 0
	global_load_dwordx4 v[92:95], v[92:93], off offset:384
	v_addc_co_u32_e32 v113, vcc, 0, v101, vcc
	v_add_co_u32_e32 v116, vcc, 0x10000, v120
	global_load_dwordx4 v[100:103], v[100:101], off offset:384
	s_nop 0
	global_load_dwordx4 v[108:111], v[120:121], off offset:384
	v_addc_co_u32_e32 v117, vcc, 0, v121, vcc
	v_add_co_u32_e32 v122, vcc, 0x20000, v120
	global_load_dwordx4 v[112:115], v[112:113], off offset:384
	s_nop 0
	global_load_dwordx4 v[116:119], v[116:117], off offset:384
	v_addc_co_u32_e32 v123, vcc, 0, v121, vcc
	v_add_co_u32_e32 v124, vcc, 0x30000, v120
	s_nop 1
	v_addc_co_u32_e32 v125, vcc, 0, v121, vcc
	global_load_dwordx4 v[120:123], v[122:123], off offset:384
	s_nop 0
	global_load_dwordx4 v[124:127], v[124:125], off offset:384
	s_branch .LBB0_480

; #define MFMA(a, b, c) __builtin_amdgcn_mfma_f32_32x32x16_bf16((a), (b), (c), 0, 0, 0)
; DI void gt_compute(const bf16* asr, const bf16* bsr, f32x16& acc0, f32x16& acc1, f32x16& acc2, f32x16& acc3) {
;   bf16x8 a[4], b0[4], b1[4], b2[4], b3[4];
; #pragma unroll
;   for (int kk = 0; kk < 4; ++kk) {
;     a[kk] = *(const bf16x8*)(asr + kk * 16);
;     b0[kk] = *(const bf16x8*)(bsr + kk * 16);
;     b1[kk] = *(const bf16x8*)(bsr + 32 * LDT + kk * 16);
;     b2[kk] = *(const bf16x8*)(bsr + 64 * LDT + kk * 16);
;     b3[kk] = *(const bf16x8*)(bsr + 96 * LDT + kk * 16);
;   }
;   __builtin_amdgcn_sched_barrier(0);
;   __builtin_amdgcn_s_setprio(2);
; #pragma unroll
;   for (int kk = 0; kk < 4; ++kk) {
;     acc0 = MFMA(a[kk], b0[kk], acc0); acc1 = MFMA(a[kk], b1[kk], acc1); acc2 = MFMA(a[kk], b2[kk], acc2); acc3 = MFMA(a[kk], b3[kk], acc3);
;   }
;   __builtin_amdgcn_s_setprio(0);
;   __builtin_amdgcn_sched_barrier(0);
; DI void gemm_mainloop(const bf16* __restrict__ A, int lda, const bf16* __restrict__ Bt, int ldb, int K, int m0, int n0,
;                       bf16* As, bf16* Bs, f32x16& acc0, f32x16& acc1, f32x16& acc2, f32x16& acc3) {
;     ...
;   for (int k0 = 0; k0 < K; k0 += 128) {
;     __syncthreads();
;     gt_store(t0, asw, bsw);
;     __syncthreads();
;     if (k0 + 128 < K) gt_load(t0, ap, bp, lda, ldb, KW(k0 + 128));
;     gt_compute(asr, bsr, acc0, acc1, acc2, acc3);
;     __syncthreads();
;     gt_store(t1, asw, bsw);
;     __syncthreads();
;     if (k0 + 192 < K) gt_load(t1, ap, bp, lda, ldb, KW(k0 + 192));
;     gt_compute(asr, bsr, acc0, acc1, acc2, acc3);
.LBB0_613:
	ds_read_b128 v[156:159], v144
	ds_read_b128 v[162:165], v144 offset:32
	ds_read_b128 v[166:169], v128 offset:18432
	ds_read_b128 v[170:173], v128 offset:18464
	ds_read_b128 v[174:177], v128 offset:23040
	ds_read_b128 v[178:181], v128 offset:23072
	ds_read_b128 v[182:185], v128 offset:27648
	ds_read_b128 v[186:189], v128 offset:27680
	ds_read_b128 v[190:193], v128 offset:32256
	ds_read_b128 v[194:197], v128 offset:32288
	ds_read_b128 v[198:201], v144 offset:64
	ds_read_b128 v[202:205], v144 offset:96
	ds_read_b128 v[206:209], v128 offset:18496
	ds_read_b128 v[210:213], v128 offset:18528
	ds_read_b128 v[214:217], v128 offset:23104
	ds_read_b128 v[228:231], v128 offset:23136
	ds_read_b128 v[232:235], v128 offset:27712
	ds_read_b128 v[236:239], v128 offset:27744
	ds_read_b128 v[240:243], v128 offset:32320
	ds_read_b128 v[244:247], v128 offset:32352
	s_waitcnt lgkmcnt(14)
	v_mfma_f32_32x32x16_bf16 v[32:47], v[156:159], v[166:169], v[32:47]
	v_mfma_f32_32x32x16_bf16 v[48:63], v[156:159], v[174:177], v[48:63]
	s_waitcnt lgkmcnt(13)
	v_mfma_f32_32x32x16_bf16 v[16:31], v[156:159], v[182:185], v[16:31]
	s_waitcnt lgkmcnt(11)
	v_mfma_f32_32x32x16_bf16 v[0:15], v[156:159], v[190:193], v[0:15]
	v_mfma_f32_32x32x16_bf16 v[32:47], v[162:165], v[170:173], v[32:47]
	v_mfma_f32_32x32x16_bf16 v[48:63], v[162:165], v[178:181], v[48:63]
	v_mfma_f32_32x32x16_bf16 v[16:31], v[162:165], v[186:189], v[16:31]
	s_waitcnt lgkmcnt(10)
	v_mfma_f32_32x32x16_bf16 v[0:15], v[162:165], v[194:197], v[0:15]
	s_waitcnt lgkmcnt(7)
	v_mfma_f32_32x32x16_bf16 v[32:47], v[198:201], v[206:209], v[32:47]
	s_waitcnt lgkmcnt(5)
	v_mfma_f32_32x32x16_bf16 v[48:63], v[198:201], v[214:217], v[48:63]
	s_waitcnt lgkmcnt(3)
	v_mfma_f32_32x32x16_bf16 v[16:31], v[198:201], v[232:235], v[16:31]
	s_waitcnt lgkmcnt(1)
	v_mfma_f32_32x32x16_bf16 v[0:15], v[198:201], v[240:243], v[0:15]
	v_mfma_f32_32x32x16_bf16 v[32:47], v[202:205], v[210:213], v[32:47]
	v_mfma_f32_32x32x16_bf16 v[48:63], v[202:205], v[228:231], v[48:63]
	v_mfma_f32_32x32x16_bf16 v[16:31], v[202:205], v[236:239], v[16:31]
	s_waitcnt lgkmcnt(0)
	v_mfma_f32_32x32x16_bf16 v[0:15], v[202:205], v[244:247], v[0:15]
	s_add_i32 s0, s60, 0xffffff80
	s_cmpk_lt_u32 s0, 0x380
	s_mov_b64 s[58:59], s[60:61]
	s_cbranch_scc0 .LBB0_618

; #define MFMA(a, b, c) __builtin_amdgcn_mfma_f32_32x32x16_bf16((a), (b), (c), 0, 0, 0)
; DI void gt_compute(const bf16* asr, const bf16* bsr, f32x16& acc0, f32x16& acc1, f32x16& acc2, f32x16& acc3) {
;   bf16x8 a[4], b0[4], b1[4], b2[4], b3[4];
; #pragma unroll
;   for (int kk = 0; kk < 4; ++kk) {
;     a[kk] = *(const bf16x8*)(asr + kk * 16);
;     b0[kk] = *(const bf16x8*)(bsr + kk * 16);
;     b1[kk] = *(const bf16x8*)(bsr + 32 * LDT + kk * 16);
;     b2[kk] = *(const bf16x8*)(bsr + 64 * LDT + kk * 16);
;     b3[kk] = *(const bf16x8*)(bsr + 96 * LDT + kk * 16);
;   }
;   __builtin_amdgcn_sched_barrier(0);
;   __builtin_amdgcn_s_setprio(2);
; #pragma unroll
;   for (int kk = 0; kk < 4; ++kk) {
;     acc0 = MFMA(a[kk], b0[kk], acc0); acc1 = MFMA(a[kk], b1[kk], acc1); acc2 = MFMA(a[kk], b2[kk], acc2); acc3 = MFMA(a[kk], b3[kk], acc3);
;   }
;   __builtin_amdgcn_s_setprio(0);
;   __builtin_amdgcn_sched_barrier(0);
; DI void gemm_mainloop(const bf16* __restrict__ A, int lda, const bf16* __restrict__ Bt, int ldb, int K, int m0, int n0,
;                       bf16* As, bf16* Bs, f32x16& acc0, f32x16& acc1, f32x16& acc2, f32x16& acc3) {
;     ...
;   for (int k0 = 0; k0 < K; k0 += 128) {
;     __syncthreads();
;     gt_store(t0, asw, bsw);
;     __syncthreads();
;     if (k0 + 128 < K) gt_load(t0, ap, bp, lda, ldb, KW(k0 + 128));
;     gt_compute(asr, bsr, acc0, acc1, acc2, acc3);
;     __syncthreads();
;     gt_store(t1, asw, bsw);
;     __syncthreads();
;     if (k0 + 192 < K) gt_load(t1, ap, bp, lda, ldb, KW(k0 + 192));
;     gt_compute(asr, bsr, acc0, acc1, acc2, acc3);
.LBB0_616:
	ds_read_b128 v[156:159], v144
	ds_read_b128 v[162:165], v144 offset:32
	ds_read_b128 v[166:169], v128 offset:18432
	ds_read_b128 v[170:173], v128 offset:18464
	ds_read_b128 v[174:177], v128 offset:23040
	ds_read_b128 v[178:181], v128 offset:23072
	ds_read_b128 v[182:185], v128 offset:27648
	ds_read_b128 v[186:189], v128 offset:27680
	ds_read_b128 v[190:193], v128 offset:32256
	ds_read_b128 v[194:197], v128 offset:32288
	ds_read_b128 v[198:201], v144 offset:64
	ds_read_b128 v[202:205], v144 offset:96
	ds_read_b128 v[206:209], v128 offset:18496
	ds_read_b128 v[210:213], v128 offset:18528
	ds_read_b128 v[214:217], v128 offset:23104
	ds_read_b128 v[228:231], v128 offset:23136
	ds_read_b128 v[232:235], v128 offset:27712
	ds_read_b128 v[236:239], v128 offset:27744
	ds_read_b128 v[240:243], v128 offset:32320
	ds_read_b128 v[244:247], v128 offset:32352
	s_waitcnt lgkmcnt(14)
	v_mfma_f32_32x32x16_bf16 v[32:47], v[156:159], v[166:169], v[32:47]
	v_mfma_f32_32x32x16_bf16 v[48:63], v[156:159], v[174:177], v[48:63]
	s_waitcnt lgkmcnt(13)
	v_mfma_f32_32x32x16_bf16 v[16:31], v[156:159], v[182:185], v[16:31]
	s_waitcnt lgkmcnt(11)
	v_mfma_f32_32x32x16_bf16 v[0:15], v[156:159], v[190:193], v[0:15]
	v_mfma_f32_32x32x16_bf16 v[32:47], v[162:165], v[170:173], v[32:47]
	v_mfma_f32_32x32x16_bf16 v[48:63], v[162:165], v[178:181], v[48:63]
	v_mfma_f32_32x32x16_bf16 v[16:31], v[162:165], v[186:189], v[16:31]
	s_waitcnt lgkmcnt(10)
	v_mfma_f32_32x32x16_bf16 v[0:15], v[162:165], v[194:197], v[0:15]
	s_waitcnt lgkmcnt(7)
	v_mfma_f32_32x32x16_bf16 v[32:47], v[198:201], v[206:209], v[32:47]
	s_waitcnt lgkmcnt(5)
	v_mfma_f32_32x32x16_bf16 v[48:63], v[198:201], v[214:217], v[48:63]
	s_waitcnt lgkmcnt(3)
	v_mfma_f32_32x32x16_bf16 v[16:31], v[198:201], v[232:235], v[16:31]
	s_waitcnt lgkmcnt(1)
	v_mfma_f32_32x32x16_bf16 v[0:15], v[198:201], v[240:243], v[0:15]
	v_mfma_f32_32x32x16_bf16 v[32:47], v[202:205], v[210:213], v[32:47]
	v_mfma_f32_32x32x16_bf16 v[48:63], v[202:205], v[228:231], v[48:63]
	v_mfma_f32_32x32x16_bf16 v[16:31], v[202:205], v[236:239], v[16:31]
	s_waitcnt lgkmcnt(0)
	v_mfma_f32_32x32x16_bf16 v[0:15], v[202:205], v[244:247], v[0:15]
	s_cmpk_gt_u32 s58, 0x33f
	s_barrier
	s_waitcnt vmcnt(5)
	ds_write_b128 v142, v[100:103]
	ds_write_b128 v142, v[88:91] offset:4608
	ds_write_b128 v142, v[92:95] offset:9216
	s_waitcnt vmcnt(3)
	ds_write_b128 v142, v[112:115] offset:13824
	ds_write_b128 v142, v[108:111] offset:18432
	s_waitcnt vmcnt(2)
	ds_write_b128 v142, v[116:119] offset:23040
	s_waitcnt vmcnt(1)
	ds_write_b128 v142, v[120:123] offset:27648
	s_waitcnt vmcnt(0)
	ds_write_b128 v142, v[124:127] offset:32256
	s_waitcnt lgkmcnt(0)
	s_barrier
	s_cbranch_scc1 .LBB0_613
	s_cmp_lt_i32 s58, s87
	s_cselect_b32 s0, 0, -1
	s_cselect_b32 s1, 0, 0xfffffc00
	s_add_u32 s6, s28, s58
	s_addc_u32 s7, s29, s59
	s_add_u32 s6, s6, s1
	s_addc_u32 s7, s7, s0
	s_lshl_b64 s[6:7], s[6:7], 1
	v_lshl_add_u64 v[100:101], v[138:139], 0, s[6:7]
	v_add_co_u32_e32 v88, vcc, s68, v100
	v_lshl_add_u64 v[120:121], v[140:141], 0, s[6:7]
	s_nop 0
	v_addc_co_u32_e32 v89, vcc, 0, v101, vcc
	v_add_co_u32_e32 v92, vcc, 0x20000, v100
	s_nop 1
	v_addc_co_u32_e32 v93, vcc, 0, v101, vcc
	v_add_co_u32_e32 v112, vcc, 0x30000, v100
	global_load_dwordx4 v[88:91], v[88:89], off offset:384
	s_nop 0
	global_load_dwordx4 v[92:95], v[92:93], off offset:384
	v_addc_co_u32_e32 v113, vcc, 0, v101, vcc
	v_add_co_u32_e32 v116, vcc, 0x10000, v120
	global_load_dwordx4 v[100:103], v[100:101], off offset:384
	s_nop 0
	global_load_dwordx4 v[108:111], v[120:121], off offset:384
	v_addc_co_u32_e32 v117, vcc, 0, v121, vcc
	v_add_co_u32_e32 v122, vcc, 0x20000, v120
	global_load_dwordx4 v[112:115], v[112:113], off offset:384
	s_nop 0
	global_load_dwordx4 v[116:119], v[116:117], off offset:384
	v_addc_co_u32_e32 v123, vcc, 0, v121, vcc
	v_add_co_u32_e32 v124, vcc, 0x30000, v120
	s_nop 1
	v_addc_co_u32_e32 v125, vcc, 0, v121, vcc
	global_load_dwordx4 v[120:123], v[122:123], off offset:384
	s_nop 0
	global_load_dwordx4 v[124:127], v[124:125], off offset:384
	s_branch .LBB0_613

; #define MFMA(a, b, c) __builtin_amdgcn_mfma_f32_32x32x16_bf16((a), (b), (c), 0, 0, 0)
; DI void gt_compute(const bf16* asr, const bf16* bsr, f32x16& acc0, f32x16& acc1, f32x16& acc2, f32x16& acc3) {
;   bf16x8 a[4], b0[4], b1[4], b2[4], b3[4];
; #pragma unroll
;   for (int kk = 0; kk < 4; ++kk) {
;     a[kk] = *(const bf16x8*)(asr + kk * 16);
;     b0[kk] = *(const bf16x8*)(bsr + kk * 16);
;     b1[kk] = *(const bf16x8*)(bsr + 32 * LDT + kk * 16);
;     b2[kk] = *(const bf16x8*)(bsr + 64 * LDT + kk * 16);
;     b3[kk] = *(const bf16x8*)(bsr + 96 * LDT + kk * 16);
;   }
;   __builtin_amdgcn_sched_barrier(0);
;   __builtin_amdgcn_s_setprio(2);
; #pragma unroll
;   for (int kk = 0; kk < 4; ++kk) {
;     acc0 = MFMA(a[kk], b0[kk], acc0); acc1 = MFMA(a[kk], b1[kk], acc1); acc2 = MFMA(a[kk], b2[kk], acc2); acc3 = MFMA(a[kk], b3[kk], acc3);
;   }
;   __builtin_amdgcn_s_setprio(0);
;   __builtin_amdgcn_sched_barrier(0);
; DI void gemm_mainloop(const bf16* __restrict__ A, int lda, const bf16* __restrict__ Bt, int ldb, int K, int m0, int n0,
;                       bf16* As, bf16* Bs, f32x16& acc0, f32x16& acc1, f32x16& acc2, f32x16& acc3) {
;     ...
;   for (int k0 = 0; k0 < K; k0 += 128) {
;     __syncthreads();
;     gt_store(t0, asw, bsw);
;     __syncthreads();
;     if (k0 + 128 < K) gt_load(t0, ap, bp, lda, ldb, KW(k0 + 128));
;     gt_compute(asr, bsr, acc0, acc1, acc2, acc3);
;     __syncthreads();
;     gt_store(t1, asw, bsw);
;     __syncthreads();
;     if (k0 + 192 < K) gt_load(t1, ap, bp, lda, ldb, KW(k0 + 192));
;     gt_compute(asr, bsr, acc0, acc1, acc2, acc3);
.LBB0_950:
	ds_read_b128 v[156:159], v152
	ds_read_b128 v[162:165], v152 offset:32
	ds_read_b128 v[174:177], v130 offset:18432
	ds_read_b128 v[178:181], v130 offset:18464
	ds_read_b128 v[182:185], v130 offset:23040
	ds_read_b128 v[186:189], v130 offset:23072
	ds_read_b128 v[190:193], v130 offset:27648
	ds_read_b128 v[194:197], v130 offset:27680
	ds_read_b128 v[198:201], v130 offset:32256
	ds_read_b128 v[202:205], v130 offset:32288
	ds_read_b128 v[206:209], v152 offset:64
	ds_read_b128 v[210:213], v152 offset:96
	ds_read_b128 v[214:217], v130 offset:18496
	ds_read_b128 v[226:229], v130 offset:18528
	ds_read_b128 v[230:233], v130 offset:23104
	ds_read_b128 v[234:237], v130 offset:23136
	ds_read_b128 v[238:241], v130 offset:27712
	ds_read_b128 v[242:245], v130 offset:27744
	ds_read_b128 v[246:249], v130 offset:32320
	ds_read_b128 v[250:253], v130 offset:32352
	s_waitcnt lgkmcnt(14)
	v_mfma_f32_32x32x16_bf16 v[48:63], v[156:159], v[174:177], v[48:63]
	v_mfma_f32_32x32x16_bf16 v[16:31], v[156:159], v[182:185], v[16:31]
	s_waitcnt lgkmcnt(13)
	v_mfma_f32_32x32x16_bf16 v[32:47], v[156:159], v[190:193], v[32:47]
	s_waitcnt lgkmcnt(11)
	v_mfma_f32_32x32x16_bf16 v[0:15], v[156:159], v[198:201], v[0:15]
	v_mfma_f32_32x32x16_bf16 v[48:63], v[162:165], v[178:181], v[48:63]
	v_mfma_f32_32x32x16_bf16 v[16:31], v[162:165], v[186:189], v[16:31]
	v_mfma_f32_32x32x16_bf16 v[32:47], v[162:165], v[194:197], v[32:47]
	s_waitcnt lgkmcnt(10)
	v_mfma_f32_32x32x16_bf16 v[0:15], v[162:165], v[202:205], v[0:15]
	s_waitcnt lgkmcnt(7)
	v_mfma_f32_32x32x16_bf16 v[48:63], v[206:209], v[214:217], v[48:63]
	s_waitcnt lgkmcnt(5)
	v_mfma_f32_32x32x16_bf16 v[16:31], v[206:209], v[230:233], v[16:31]
	s_waitcnt lgkmcnt(3)
	v_mfma_f32_32x32x16_bf16 v[32:47], v[206:209], v[238:241], v[32:47]
	s_waitcnt lgkmcnt(1)
	v_mfma_f32_32x32x16_bf16 v[0:15], v[206:209], v[246:249], v[0:15]
	v_mfma_f32_32x32x16_bf16 v[48:63], v[210:213], v[226:229], v[48:63]
	v_mfma_f32_32x32x16_bf16 v[16:31], v[210:213], v[234:237], v[16:31]
	v_mfma_f32_32x32x16_bf16 v[32:47], v[210:213], v[242:245], v[32:47]
	s_waitcnt lgkmcnt(0)
	v_mfma_f32_32x32x16_bf16 v[0:15], v[210:213], v[250:253], v[0:15]
	s_add_i32 s6, s50, 0xffffff80
	s_cmpk_lt_u32 s6, 0x380
	s_mov_b64 s[48:49], s[50:51]
	s_cbranch_scc0 .LBB0_955

; #define MFMA(a, b, c) __builtin_amdgcn_mfma_f32_32x32x16_bf16((a), (b), (c), 0, 0, 0)
; DI void gt_compute(const bf16* asr, const bf16* bsr, f32x16& acc0, f32x16& acc1, f32x16& acc2, f32x16& acc3) {
;   bf16x8 a[4], b0[4], b1[4], b2[4], b3[4];
; #pragma unroll
;   for (int kk = 0; kk < 4; ++kk) {
;     a[kk] = *(const bf16x8*)(asr + kk * 16);
;     b0[kk] = *(const bf16x8*)(bsr + kk * 16);
;     b1[kk] = *(const bf16x8*)(bsr + 32 * LDT + kk * 16);
;     b2[kk] = *(const bf16x8*)(bsr + 64 * LDT + kk * 16);
;     b3[kk] = *(const bf16x8*)(bsr + 96 * LDT + kk * 16);
;   }
;   __builtin_amdgcn_sched_barrier(0);
;   __builtin_amdgcn_s_setprio(2);
; #pragma unroll
;   for (int kk = 0; kk < 4; ++kk) {
;     acc0 = MFMA(a[kk], b0[kk], acc0); acc1 = MFMA(a[kk], b1[kk], acc1); acc2 = MFMA(a[kk], b2[kk], acc2); acc3 = MFMA(a[kk], b3[kk], acc3);
;   }
;   __builtin_amdgcn_s_setprio(0);
;   __builtin_amdgcn_sched_barrier(0);
; DI void gemm_mainloop(const bf16* __restrict__ A, int lda, const bf16* __restrict__ Bt, int ldb, int K, int m0, int n0,
;                       bf16* As, bf16* Bs, f32x16& acc0, f32x16& acc1, f32x16& acc2, f32x16& acc3) {
;     ...
;   for (int k0 = 0; k0 < K; k0 += 128) {
;     __syncthreads();
;     gt_store(t0, asw, bsw);
;     __syncthreads();
;     if (k0 + 128 < K) gt_load(t0, ap, bp, lda, ldb, KW(k0 + 128));
;     gt_compute(asr, bsr, acc0, acc1, acc2, acc3);
;     __syncthreads();
;     gt_store(t1, asw, bsw);
;     __syncthreads();
;     if (k0 + 192 < K) gt_load(t1, ap, bp, lda, ldb, KW(k0 + 192));
;     gt_compute(asr, bsr, acc0, acc1, acc2, acc3);
.LBB0_953:
	ds_read_b128 v[174:177], v152
	ds_read_b128 v[178:181], v152 offset:32
	ds_read_b128 v[182:185], v130 offset:18432
	ds_read_b128 v[186:189], v130 offset:18464
	ds_read_b128 v[190:193], v130 offset:23040
	ds_read_b128 v[194:197], v130 offset:23072
	ds_read_b128 v[198:201], v130 offset:27648
	ds_read_b128 v[202:205], v130 offset:27680
	ds_read_b128 v[206:209], v130 offset:32256
	ds_read_b128 v[210:213], v130 offset:32288
	ds_read_b128 v[214:217], v152 offset:64
	ds_read_b128 v[226:229], v152 offset:96
	ds_read_b128 v[230:233], v130 offset:18496
	ds_read_b128 v[234:237], v130 offset:18528
	ds_read_b128 v[238:241], v130 offset:23104
	ds_read_b128 v[242:245], v130 offset:23136
	ds_read_b128 v[246:249], v130 offset:27712
	ds_read_b128 v[250:253], v130 offset:27744
	ds_read_b128 v[156:159], v130 offset:32320
	ds_read_b128 v[162:165], v130 offset:32352
	s_waitcnt lgkmcnt(14)
	v_mfma_f32_32x32x16_bf16 v[48:63], v[174:177], v[182:185], v[48:63]
	v_mfma_f32_32x32x16_bf16 v[16:31], v[174:177], v[190:193], v[16:31]
	s_waitcnt lgkmcnt(13)
	v_mfma_f32_32x32x16_bf16 v[32:47], v[174:177], v[198:201], v[32:47]
	s_waitcnt lgkmcnt(11)
	v_mfma_f32_32x32x16_bf16 v[0:15], v[174:177], v[206:209], v[0:15]
	v_mfma_f32_32x32x16_bf16 v[48:63], v[178:181], v[186:189], v[48:63]
	v_mfma_f32_32x32x16_bf16 v[16:31], v[178:181], v[194:197], v[16:31]
	v_mfma_f32_32x32x16_bf16 v[32:47], v[178:181], v[202:205], v[32:47]
	s_waitcnt lgkmcnt(10)
	v_mfma_f32_32x32x16_bf16 v[0:15], v[178:181], v[210:213], v[0:15]
	s_waitcnt lgkmcnt(7)
	v_mfma_f32_32x32x16_bf16 v[48:63], v[214:217], v[230:233], v[48:63]
	s_waitcnt lgkmcnt(5)
	v_mfma_f32_32x32x16_bf16 v[16:31], v[214:217], v[238:241], v[16:31]
	s_waitcnt lgkmcnt(3)
	v_mfma_f32_32x32x16_bf16 v[32:47], v[214:217], v[246:249], v[32:47]
	s_waitcnt lgkmcnt(1)
	v_mfma_f32_32x32x16_bf16 v[0:15], v[214:217], v[156:159], v[0:15]
	v_mfma_f32_32x32x16_bf16 v[48:63], v[226:229], v[234:237], v[48:63]
	v_mfma_f32_32x32x16_bf16 v[16:31], v[226:229], v[242:245], v[16:31]
	v_mfma_f32_32x32x16_bf16 v[32:47], v[226:229], v[250:253], v[32:47]
	s_waitcnt lgkmcnt(0)
	v_mfma_f32_32x32x16_bf16 v[0:15], v[226:229], v[162:165], v[0:15]
	s_cmpk_gt_u32 s48, 0x33f
	s_barrier
	s_waitcnt vmcnt(5)
	ds_write_b128 v150, v[100:103]
	ds_write_b128 v150, v[88:91] offset:4608
	ds_write_b128 v150, v[92:95] offset:9216
	s_waitcnt vmcnt(3)
	ds_write_b128 v150, v[112:115] offset:13824
	ds_write_b128 v150, v[108:111] offset:18432
	s_waitcnt vmcnt(2)
	ds_write_b128 v150, v[116:119] offset:23040
	s_waitcnt vmcnt(1)
	ds_write_b128 v150, v[120:123] offset:27648
	s_waitcnt vmcnt(0)
	ds_write_b128 v150, v[124:127] offset:32256
	s_waitcnt lgkmcnt(0)
	s_barrier
	s_cbranch_scc1 .LBB0_950
	s_cmp_lt_i32 s48, s31
	s_cselect_b32 s7, 0, -1
	s_cselect_b32 s6, 0, 0xfffffc00
	s_add_u32 s48, s28, s48
	s_addc_u32 s49, s29, s49
	s_add_u32 s6, s48, s6
	s_addc_u32 s7, s49, s7
	s_lshl_b64 s[6:7], s[6:7], 1
	v_lshl_add_u64 v[100:101], v[146:147], 0, s[6:7]
	v_add_co_u32_e32 v88, vcc, s59, v100
	v_lshl_add_u64 v[120:121], v[148:149], 0, s[6:7]
	s_nop 0
	v_addc_co_u32_e32 v89, vcc, 0, v101, vcc
	v_add_co_u32_e32 v92, vcc, 0x20000, v100
	s_nop 1
	v_addc_co_u32_e32 v93, vcc, 0, v101, vcc
	v_add_co_u32_e32 v112, vcc, 0x30000, v100
	global_load_dwordx4 v[88:91], v[88:89], off offset:384
	s_nop 0
	global_load_dwordx4 v[92:95], v[92:93], off offset:384
	v_addc_co_u32_e32 v113, vcc, 0, v101, vcc
	v_add_co_u32_e32 v116, vcc, 0x10000, v120
	global_load_dwordx4 v[100:103], v[100:101], off offset:384
	s_nop 0
	global_load_dwordx4 v[108:111], v[120:121], off offset:384
	v_addc_co_u32_e32 v117, vcc, 0, v121, vcc
	v_add_co_u32_e32 v122, vcc, 0x20000, v120
	global_load_dwordx4 v[112:115], v[112:113], off offset:384
	s_nop 0
	global_load_dwordx4 v[116:119], v[116:117], off offset:384
	v_addc_co_u32_e32 v123, vcc, 0, v121, vcc
	v_add_co_u32_e32 v124, vcc, 0x30000, v120
	s_nop 1
	v_addc_co_u32_e32 v125, vcc, 0, v121, vcc
	global_load_dwordx4 v[120:123], v[122:123], off offset:384
	s_nop 0
	global_load_dwordx4 v[124:127], v[124:125], off offset:384
	s_branch .LBB0_950

; #define MFMA(a, b, c) __builtin_amdgcn_mfma_f32_32x32x16_bf16((a), (b), (c), 0, 0, 0)
; DI void gt_compute(const bf16* asr, const bf16* bsr, f32x16& acc0, f32x16& acc1, f32x16& acc2, f32x16& acc3) {
;   bf16x8 a[4], b0[4], b1[4], b2[4], b3[4];
; #pragma unroll
;   for (int kk = 0; kk < 4; ++kk) {
;     a[kk] = *(const bf16x8*)(asr + kk * 16);
;     b0[kk] = *(const bf16x8*)(bsr + kk * 16);
;     b1[kk] = *(const bf16x8*)(bsr + 32 * LDT + kk * 16);
;     b2[kk] = *(const bf16x8*)(bsr + 64 * LDT + kk * 16);
;     b3[kk] = *(const bf16x8*)(bsr + 96 * LDT + kk * 16);
;   }
;   __builtin_amdgcn_sched_barrier(0);
;   __builtin_amdgcn_s_setprio(2);
; #pragma unroll
;   for (int kk = 0; kk < 4; ++kk) {
;     acc0 = MFMA(a[kk], b0[kk], acc0); acc1 = MFMA(a[kk], b1[kk], acc1); acc2 = MFMA(a[kk], b2[kk], acc2); acc3 = MFMA(a[kk], b3[kk], acc3);
;   }
;   __builtin_amdgcn_s_setprio(0);
;   __builtin_amdgcn_sched_barrier(0);
; DI void gemm_mainloop(const bf16* __restrict__ A, int lda, const bf16* __restrict__ Bt, int ldb, int K, int m0, int n0,
;                       bf16* As, bf16* Bs, f32x16& acc0, f32x16& acc1, f32x16& acc2, f32x16& acc3) {
;     ...
;   for (int k0 = 0; k0 < K; k0 += 128) {
;     __syncthreads();
;     gt_store(t0, asw, bsw);
;     __syncthreads();
;     if (k0 + 128 < K) gt_load(t0, ap, bp, lda, ldb, KW(k0 + 128));
;     gt_compute(asr, bsr, acc0, acc1, acc2, acc3);
;     __syncthreads();
;     gt_store(t1, asw, bsw);
;     __syncthreads();
;     if (k0 + 192 < K) gt_load(t1, ap, bp, lda, ldb, KW(k0 + 192));
;     gt_compute(asr, bsr, acc0, acc1, acc2, acc3);
.LBB0_1318:
	ds_read_b128 v[142:145], v138
	ds_read_b128 v[146:149], v138 offset:32
	ds_read_b128 v[150:153], v128 offset:18432
	ds_read_b128 v[154:157], v128 offset:18464
	ds_read_b128 v[162:165], v128 offset:23040
	ds_read_b128 v[166:169], v128 offset:23072
	ds_read_b128 v[170:173], v128 offset:27648
	ds_read_b128 v[174:177], v128 offset:27680
	ds_read_b128 v[178:181], v128 offset:32256
	ds_read_b128 v[182:185], v128 offset:32288
	ds_read_b128 v[186:189], v138 offset:64
	ds_read_b128 v[190:193], v138 offset:96
	ds_read_b128 v[194:197], v128 offset:18496
	ds_read_b128 v[198:201], v128 offset:18528
	ds_read_b128 v[202:205], v128 offset:23104
	ds_read_b128 v[206:209], v128 offset:23136
	ds_read_b128 v[210:213], v128 offset:27712
	ds_read_b128 v[214:217], v128 offset:27744
	ds_read_b128 v[226:229], v128 offset:32320
	ds_read_b128 v[230:233], v128 offset:32352
	s_waitcnt lgkmcnt(14)
	v_mfma_f32_32x32x16_bf16 v[48:63], v[142:145], v[150:153], v[48:63]
	v_mfma_f32_32x32x16_bf16 v[32:47], v[142:145], v[162:165], v[32:47]
	s_waitcnt lgkmcnt(13)
	v_mfma_f32_32x32x16_bf16 v[16:31], v[142:145], v[170:173], v[16:31]
	s_waitcnt lgkmcnt(11)
	v_mfma_f32_32x32x16_bf16 v[0:15], v[142:145], v[178:181], v[0:15]
	v_mfma_f32_32x32x16_bf16 v[48:63], v[146:149], v[154:157], v[48:63]
	v_mfma_f32_32x32x16_bf16 v[32:47], v[146:149], v[166:169], v[32:47]
	v_mfma_f32_32x32x16_bf16 v[16:31], v[146:149], v[174:177], v[16:31]
	s_waitcnt lgkmcnt(10)
	v_mfma_f32_32x32x16_bf16 v[0:15], v[146:149], v[182:185], v[0:15]
	s_waitcnt lgkmcnt(7)
	v_mfma_f32_32x32x16_bf16 v[48:63], v[186:189], v[194:197], v[48:63]
	s_waitcnt lgkmcnt(5)
	v_mfma_f32_32x32x16_bf16 v[32:47], v[186:189], v[202:205], v[32:47]
	s_waitcnt lgkmcnt(3)
	v_mfma_f32_32x32x16_bf16 v[16:31], v[186:189], v[210:213], v[16:31]
	s_waitcnt lgkmcnt(1)
	v_mfma_f32_32x32x16_bf16 v[0:15], v[186:189], v[226:229], v[0:15]
	v_mfma_f32_32x32x16_bf16 v[48:63], v[190:193], v[198:201], v[48:63]
	v_mfma_f32_32x32x16_bf16 v[32:47], v[190:193], v[206:209], v[32:47]
	v_mfma_f32_32x32x16_bf16 v[16:31], v[190:193], v[214:217], v[16:31]
	s_waitcnt lgkmcnt(0)
	v_mfma_f32_32x32x16_bf16 v[0:15], v[190:193], v[230:233], v[0:15]
	s_add_i32 s0, s16, 0xffffff80
	s_cmpk_lt_u32 s0, 0x380
	s_mov_b64 s[14:15], s[16:17]
	s_cbranch_scc0 .LBB0_1316

; #define MFMA(a, b, c) __builtin_amdgcn_mfma_f32_32x32x16_bf16((a), (b), (c), 0, 0, 0)
; DI void gt_compute(const bf16* asr, const bf16* bsr, f32x16& acc0, f32x16& acc1, f32x16& acc2, f32x16& acc3) {
;   bf16x8 a[4], b0[4], b1[4], b2[4], b3[4];
; #pragma unroll
;   for (int kk = 0; kk < 4; ++kk) {
;     a[kk] = *(const bf16x8*)(asr + kk * 16);
;     b0[kk] = *(const bf16x8*)(bsr + kk * 16);
;     b1[kk] = *(const bf16x8*)(bsr + 32 * LDT + kk * 16);
;     b2[kk] = *(const bf16x8*)(bsr + 64 * LDT + kk * 16);
;     b3[kk] = *(const bf16x8*)(bsr + 96 * LDT + kk * 16);
;   }
;   __builtin_amdgcn_sched_barrier(0);
;   __builtin_amdgcn_s_setprio(2);
; #pragma unroll
;   for (int kk = 0; kk < 4; ++kk) {
;     acc0 = MFMA(a[kk], b0[kk], acc0); acc1 = MFMA(a[kk], b1[kk], acc1); acc2 = MFMA(a[kk], b2[kk], acc2); acc3 = MFMA(a[kk], b3[kk], acc3);
;   }
;   __builtin_amdgcn_s_setprio(0);
;   __builtin_amdgcn_sched_barrier(0);
; DI void gemm_mainloop(const bf16* __restrict__ A, int lda, const bf16* __restrict__ Bt, int ldb, int K, int m0, int n0,
;                       bf16* As, bf16* Bs, f32x16& acc0, f32x16& acc1, f32x16& acc2, f32x16& acc3) {
;     ...
;   for (int k0 = 0; k0 < K; k0 += 128) {
;     __syncthreads();
;     gt_store(t0, asw, bsw);
;     __syncthreads();
;     if (k0 + 128 < K) gt_load(t0, ap, bp, lda, ldb, KW(k0 + 128));
;     gt_compute(asr, bsr, acc0, acc1, acc2, acc3);
;     __syncthreads();
;     gt_store(t1, asw, bsw);
;     __syncthreads();
;     if (k0 + 192 < K) gt_load(t1, ap, bp, lda, ldb, KW(k0 + 192));
;     gt_compute(asr, bsr, acc0, acc1, acc2, acc3);
.LBB0_1321:
	ds_read_b128 v[142:145], v138
	ds_read_b128 v[146:149], v138 offset:32
	ds_read_b128 v[150:153], v128 offset:18432
	ds_read_b128 v[154:157], v128 offset:18464
	ds_read_b128 v[162:165], v128 offset:23040
	ds_read_b128 v[166:169], v128 offset:23072
	ds_read_b128 v[170:173], v128 offset:27648
	ds_read_b128 v[174:177], v128 offset:27680
	ds_read_b128 v[178:181], v128 offset:32256
	ds_read_b128 v[182:185], v128 offset:32288
	ds_read_b128 v[186:189], v138 offset:64
	ds_read_b128 v[190:193], v138 offset:96
	ds_read_b128 v[194:197], v128 offset:18496
	ds_read_b128 v[198:201], v128 offset:18528
	ds_read_b128 v[202:205], v128 offset:23104
	ds_read_b128 v[206:209], v128 offset:23136
	ds_read_b128 v[210:213], v128 offset:27712
	ds_read_b128 v[214:217], v128 offset:27744
	ds_read_b128 v[226:229], v128 offset:32320
	ds_read_b128 v[230:233], v128 offset:32352
	s_waitcnt lgkmcnt(14)
	v_mfma_f32_32x32x16_bf16 v[48:63], v[142:145], v[150:153], v[48:63]
	v_mfma_f32_32x32x16_bf16 v[32:47], v[142:145], v[162:165], v[32:47]
	s_waitcnt lgkmcnt(13)
	v_mfma_f32_32x32x16_bf16 v[16:31], v[142:145], v[170:173], v[16:31]
	s_waitcnt lgkmcnt(11)
	v_mfma_f32_32x32x16_bf16 v[0:15], v[142:145], v[178:181], v[0:15]
	v_mfma_f32_32x32x16_bf16 v[48:63], v[146:149], v[154:157], v[48:63]
	v_mfma_f32_32x32x16_bf16 v[32:47], v[146:149], v[166:169], v[32:47]
	v_mfma_f32_32x32x16_bf16 v[16:31], v[146:149], v[174:177], v[16:31]
	s_waitcnt lgkmcnt(10)
	v_mfma_f32_32x32x16_bf16 v[0:15], v[146:149], v[182:185], v[0:15]
	s_waitcnt lgkmcnt(7)
	v_mfma_f32_32x32x16_bf16 v[48:63], v[186:189], v[194:197], v[48:63]
	s_waitcnt lgkmcnt(5)
	v_mfma_f32_32x32x16_bf16 v[32:47], v[186:189], v[202:205], v[32:47]
	s_waitcnt lgkmcnt(3)
	v_mfma_f32_32x32x16_bf16 v[16:31], v[186:189], v[210:213], v[16:31]
	s_waitcnt lgkmcnt(1)
	v_mfma_f32_32x32x16_bf16 v[0:15], v[186:189], v[226:229], v[0:15]
	v_mfma_f32_32x32x16_bf16 v[48:63], v[190:193], v[198:201], v[48:63]
	v_mfma_f32_32x32x16_bf16 v[32:47], v[190:193], v[206:209], v[32:47]
	v_mfma_f32_32x32x16_bf16 v[16:31], v[190:193], v[214:217], v[16:31]
	s_waitcnt lgkmcnt(0)
	v_mfma_f32_32x32x16_bf16 v[0:15], v[190:193], v[230:233], v[0:15]
	s_cmpk_gt_u32 s14, 0x33f
	s_barrier
	s_waitcnt vmcnt(5)
	ds_write_b128 v136, v[104:107]
	ds_write_b128 v136, v[88:91] offset:4608
	ds_write_b128 v136, v[92:95] offset:9216
	s_waitcnt vmcnt(3)
	ds_write_b128 v136, v[112:115] offset:13824
	ds_write_b128 v136, v[108:111] offset:18432
	s_waitcnt vmcnt(2)
	ds_write_b128 v136, v[116:119] offset:23040
	s_waitcnt vmcnt(1)
	ds_write_b128 v136, v[120:123] offset:27648
	s_waitcnt vmcnt(0)
	ds_write_b128 v136, v[124:127] offset:32256
	s_waitcnt lgkmcnt(0)
	s_barrier
	s_cbranch_scc1 .LBB0_1318
	s_cmp_lt_i32 s14, s28
	s_cselect_b32 s0, 0, -1
	s_cselect_b32 s1, 0, 0xfffffc00
	s_add_u32 s6, s12, s14
	s_addc_u32 s7, s13, s15
	s_add_u32 s6, s6, s1
	s_addc_u32 s7, s7, s0
	s_lshl_b64 s[6:7], s[6:7], 1
	v_lshl_add_u64 v[104:105], v[132:133], 0, s[6:7]
	v_add_co_u32_e32 v88, vcc, s4, v104
	v_lshl_add_u64 v[120:121], v[134:135], 0, s[6:7]
	s_nop 0
	v_addc_co_u32_e32 v89, vcc, 0, v105, vcc
	v_add_co_u32_e32 v92, vcc, 0x20000, v104
	s_nop 1
	v_addc_co_u32_e32 v93, vcc, 0, v105, vcc
	v_add_co_u32_e32 v112, vcc, 0x30000, v104
	global_load_dwordx4 v[88:91], v[88:89], off offset:384
	s_nop 0
	global_load_dwordx4 v[92:95], v[92:93], off offset:384
	v_addc_co_u32_e32 v113, vcc, 0, v105, vcc
	v_add_co_u32_e32 v116, vcc, 0x10000, v120
	global_load_dwordx4 v[104:107], v[104:105], off offset:384
	s_nop 0
	global_load_dwordx4 v[108:111], v[120:121], off offset:384
	v_addc_co_u32_e32 v117, vcc, 0, v121, vcc
	v_add_co_u32_e32 v122, vcc, 0x20000, v120
	global_load_dwordx4 v[112:115], v[112:113], off offset:384
	s_nop 0
	global_load_dwordx4 v[116:119], v[116:117], off offset:384
	v_addc_co_u32_e32 v123, vcc, 0, v121, vcc
	v_add_co_u32_e32 v124, vcc, 0x30000, v120
	s_nop 1
	v_addc_co_u32_e32 v125, vcc, 0, v121, vcc
	global_load_dwordx4 v[120:123], v[122:123], off offset:384
	s_nop 0
	global_load_dwordx4 v[124:127], v[124:125], off offset:384
	s_branch .LBB0_1318

; #define MFMA(a, b, c) __builtin_amdgcn_mfma_f32_32x32x16_bf16((a), (b), (c), 0, 0, 0)
; DI void gt_compute(const bf16* asr, const bf16* bsr, f32x16& acc0, f32x16& acc1, f32x16& acc2, f32x16& acc3) {
;   bf16x8 a[4], b0[4], b1[4], b2[4], b3[4];
; #pragma unroll
;   for (int kk = 0; kk < 4; ++kk) {
;     a[kk] = *(const bf16x8*)(asr + kk * 16);
;     b0[kk] = *(const bf16x8*)(bsr + kk * 16);
;     b1[kk] = *(const bf16x8*)(bsr + 32 * LDT + kk * 16);
;     b2[kk] = *(const bf16x8*)(bsr + 64 * LDT + kk * 16);
;     b3[kk] = *(const bf16x8*)(bsr + 96 * LDT + kk * 16);
;   }
;   __builtin_amdgcn_sched_barrier(0);
;   __builtin_amdgcn_s_setprio(2);
; #pragma unroll
;   for (int kk = 0; kk < 4; ++kk) {
;     acc0 = MFMA(a[kk], b0[kk], acc0); acc1 = MFMA(a[kk], b1[kk], acc1); acc2 = MFMA(a[kk], b2[kk], acc2); acc3 = MFMA(a[kk], b3[kk], acc3);
;   }
;   __builtin_amdgcn_s_setprio(0);
;   __builtin_amdgcn_sched_barrier(0);
; DI void gemm_mainloop(const bf16* __restrict__ A, int lda, const bf16* __restrict__ Bt, int ldb, int K, int m0, int n0,
;                       bf16* As, bf16* Bs, f32x16& acc0, f32x16& acc1, f32x16& acc2, f32x16& acc3) {
;     ...
;   for (int k0 = 0; k0 < K; k0 += 128) {
;     __syncthreads();
;     gt_store(t0, asw, bsw);
;     __syncthreads();
;     if (k0 + 128 < K) gt_load(t0, ap, bp, lda, ldb, KW(k0 + 128));
;     gt_compute(asr, bsr, acc0, acc1, acc2, acc3);
;     __syncthreads();
;     gt_store(t1, asw, bsw);
;     __syncthreads();
;     if (k0 + 192 < K) gt_load(t1, ap, bp, lda, ldb, KW(k0 + 192));
;     gt_compute(asr, bsr, acc0, acc1, acc2, acc3);
.LBB0_1436:
	ds_read_b128 v[148:151], v136
	ds_read_b128 v[152:155], v136 offset:32
	ds_read_b128 v[156:159], v128 offset:18432
	ds_read_b128 v[162:165], v128 offset:18464
	ds_read_b128 v[166:169], v128 offset:23040
	ds_read_b128 v[170:173], v128 offset:23072
	ds_read_b128 v[174:177], v128 offset:27648
	ds_read_b128 v[178:181], v128 offset:27680
	ds_read_b128 v[182:185], v128 offset:32256
	ds_read_b128 v[186:189], v128 offset:32288
	ds_read_b128 v[190:193], v136 offset:64
	ds_read_b128 v[194:197], v136 offset:96
	ds_read_b128 v[198:201], v128 offset:18496
	ds_read_b128 v[202:205], v128 offset:18528
	ds_read_b128 v[206:209], v128 offset:23104
	ds_read_b128 v[210:213], v128 offset:23136
	ds_read_b128 v[214:217], v128 offset:27712
	ds_read_b128 v[226:229], v128 offset:27744
	ds_read_b128 v[230:233], v128 offset:32320
	ds_read_b128 v[234:237], v128 offset:32352
	s_waitcnt lgkmcnt(14)
	v_mfma_f32_32x32x16_bf16 v[32:47], v[148:151], v[156:159], v[32:47]
	v_mfma_f32_32x32x16_bf16 v[48:63], v[148:151], v[166:169], v[48:63]
	s_waitcnt lgkmcnt(13)
	v_mfma_f32_32x32x16_bf16 v[16:31], v[148:151], v[174:177], v[16:31]
	s_waitcnt lgkmcnt(11)
	v_mfma_f32_32x32x16_bf16 v[0:15], v[148:151], v[182:185], v[0:15]
	v_mfma_f32_32x32x16_bf16 v[32:47], v[152:155], v[162:165], v[32:47]
	v_mfma_f32_32x32x16_bf16 v[48:63], v[152:155], v[170:173], v[48:63]
	v_mfma_f32_32x32x16_bf16 v[16:31], v[152:155], v[178:181], v[16:31]
	s_waitcnt lgkmcnt(10)
	v_mfma_f32_32x32x16_bf16 v[0:15], v[152:155], v[186:189], v[0:15]
	s_waitcnt lgkmcnt(7)
	v_mfma_f32_32x32x16_bf16 v[32:47], v[190:193], v[198:201], v[32:47]
	s_waitcnt lgkmcnt(5)
	v_mfma_f32_32x32x16_bf16 v[48:63], v[190:193], v[206:209], v[48:63]
	s_waitcnt lgkmcnt(3)
	v_mfma_f32_32x32x16_bf16 v[16:31], v[190:193], v[214:217], v[16:31]
	s_waitcnt lgkmcnt(1)
	v_mfma_f32_32x32x16_bf16 v[0:15], v[190:193], v[230:233], v[0:15]
	v_mfma_f32_32x32x16_bf16 v[32:47], v[194:197], v[202:205], v[32:47]
	v_mfma_f32_32x32x16_bf16 v[48:63], v[194:197], v[210:213], v[48:63]
	v_mfma_f32_32x32x16_bf16 v[16:31], v[194:197], v[226:229], v[16:31]
	s_waitcnt lgkmcnt(0)
	v_mfma_f32_32x32x16_bf16 v[0:15], v[194:197], v[234:237], v[0:15]
	s_add_i32 s0, s42, 0xffffff80
	s_cmpk_lt_u32 s0, 0x380
	s_mov_b64 s[40:41], s[42:43]
	s_cbranch_scc0 .LBB0_1441

; #define MFMA(a, b, c) __builtin_amdgcn_mfma_f32_32x32x16_bf16((a), (b), (c), 0, 0, 0)
; DI void gt_compute(const bf16* asr, const bf16* bsr, f32x16& acc0, f32x16& acc1, f32x16& acc2, f32x16& acc3) {
;   bf16x8 a[4], b0[4], b1[4], b2[4], b3[4];
; #pragma unroll
;   for (int kk = 0; kk < 4; ++kk) {
;     a[kk] = *(const bf16x8*)(asr + kk * 16);
;     b0[kk] = *(const bf16x8*)(bsr + kk * 16);
;     b1[kk] = *(const bf16x8*)(bsr + 32 * LDT + kk * 16);
;     b2[kk] = *(const bf16x8*)(bsr + 64 * LDT + kk * 16);
;     b3[kk] = *(const bf16x8*)(bsr + 96 * LDT + kk * 16);
;   }
;   __builtin_amdgcn_sched_barrier(0);
;   __builtin_amdgcn_s_setprio(2);
; #pragma unroll
;   for (int kk = 0; kk < 4; ++kk) {
;     acc0 = MFMA(a[kk], b0[kk], acc0); acc1 = MFMA(a[kk], b1[kk], acc1); acc2 = MFMA(a[kk], b2[kk], acc2); acc3 = MFMA(a[kk], b3[kk], acc3);
;   }
;   __builtin_amdgcn_s_setprio(0);
;   __builtin_amdgcn_sched_barrier(0);
; DI void gemm_mainloop(const bf16* __restrict__ A, int lda, const bf16* __restrict__ Bt, int ldb, int K, int m0, int n0,
;                       bf16* As, bf16* Bs, f32x16& acc0, f32x16& acc1, f32x16& acc2, f32x16& acc3) {
;     ...
;   for (int k0 = 0; k0 < K; k0 += 128) {
;     __syncthreads();
;     gt_store(t0, asw, bsw);
;     __syncthreads();
;     if (k0 + 128 < K) gt_load(t0, ap, bp, lda, ldb, KW(k0 + 128));
;     gt_compute(asr, bsr, acc0, acc1, acc2, acc3);
;     __syncthreads();
;     gt_store(t1, asw, bsw);
;     __syncthreads();
;     if (k0 + 192 < K) gt_load(t1, ap, bp, lda, ldb, KW(k0 + 192));
;     gt_compute(asr, bsr, acc0, acc1, acc2, acc3);
.LBB0_1439:
	ds_read_b128 v[148:151], v136
	ds_read_b128 v[152:155], v136 offset:32
	ds_read_b128 v[156:159], v128 offset:18432
	ds_read_b128 v[162:165], v128 offset:18464
	ds_read_b128 v[166:169], v128 offset:23040
	ds_read_b128 v[170:173], v128 offset:23072
	ds_read_b128 v[174:177], v128 offset:27648
	ds_read_b128 v[178:181], v128 offset:27680
	ds_read_b128 v[182:185], v128 offset:32256
	ds_read_b128 v[186:189], v128 offset:32288
	ds_read_b128 v[190:193], v136 offset:64
	ds_read_b128 v[194:197], v136 offset:96
	ds_read_b128 v[198:201], v128 offset:18496
	ds_read_b128 v[202:205], v128 offset:18528
	ds_read_b128 v[206:209], v128 offset:23104
	ds_read_b128 v[210:213], v128 offset:23136
	ds_read_b128 v[214:217], v128 offset:27712
	ds_read_b128 v[226:229], v128 offset:27744
	ds_read_b128 v[230:233], v128 offset:32320
	ds_read_b128 v[234:237], v128 offset:32352
	s_waitcnt lgkmcnt(14)
	v_mfma_f32_32x32x16_bf16 v[32:47], v[148:151], v[156:159], v[32:47]
	v_mfma_f32_32x32x16_bf16 v[48:63], v[148:151], v[166:169], v[48:63]
	s_waitcnt lgkmcnt(13)
	v_mfma_f32_32x32x16_bf16 v[16:31], v[148:151], v[174:177], v[16:31]
	s_waitcnt lgkmcnt(11)
	v_mfma_f32_32x32x16_bf16 v[0:15], v[148:151], v[182:185], v[0:15]
	v_mfma_f32_32x32x16_bf16 v[32:47], v[152:155], v[162:165], v[32:47]
	v_mfma_f32_32x32x16_bf16 v[48:63], v[152:155], v[170:173], v[48:63]
	v_mfma_f32_32x32x16_bf16 v[16:31], v[152:155], v[178:181], v[16:31]
	s_waitcnt lgkmcnt(10)
	v_mfma_f32_32x32x16_bf16 v[0:15], v[152:155], v[186:189], v[0:15]
	s_waitcnt lgkmcnt(7)
	v_mfma_f32_32x32x16_bf16 v[32:47], v[190:193], v[198:201], v[32:47]
	s_waitcnt lgkmcnt(5)
	v_mfma_f32_32x32x16_bf16 v[48:63], v[190:193], v[206:209], v[48:63]
	s_waitcnt lgkmcnt(3)
	v_mfma_f32_32x32x16_bf16 v[16:31], v[190:193], v[214:217], v[16:31]
	s_waitcnt lgkmcnt(1)
	v_mfma_f32_32x32x16_bf16 v[0:15], v[190:193], v[230:233], v[0:15]
	v_mfma_f32_32x32x16_bf16 v[32:47], v[194:197], v[202:205], v[32:47]
	v_mfma_f32_32x32x16_bf16 v[48:63], v[194:197], v[210:213], v[48:63]
	v_mfma_f32_32x32x16_bf16 v[16:31], v[194:197], v[226:229], v[16:31]
	s_waitcnt lgkmcnt(0)
	v_mfma_f32_32x32x16_bf16 v[0:15], v[194:197], v[234:237], v[0:15]
	s_cmpk_gt_u32 s40, 0x33f
	s_barrier
	s_waitcnt vmcnt(5)
	ds_write_b128 v134, v[100:103]
	ds_write_b128 v134, v[88:91] offset:4608
	ds_write_b128 v134, v[92:95] offset:9216
	s_waitcnt vmcnt(3)
	ds_write_b128 v134, v[112:115] offset:13824
	ds_write_b128 v134, v[108:111] offset:18432
	s_waitcnt vmcnt(2)
	ds_write_b128 v134, v[116:119] offset:23040
	s_waitcnt vmcnt(1)
	ds_write_b128 v134, v[120:123] offset:27648
	s_waitcnt vmcnt(0)
	ds_write_b128 v134, v[124:127] offset:32256
	s_waitcnt lgkmcnt(0)
	s_barrier
	s_cbranch_scc1 .LBB0_1436
	s_cmp_lt_i32 s40, s87
	s_cselect_b32 s1, 0, -1
	s_cselect_b32 s0, 0, 0xfffffc00
	s_add_u32 s2, s28, s40
	s_addc_u32 s3, s29, s41
	s_add_u32 s0, s2, s0
	s_addc_u32 s1, s3, s1
	s_lshl_b64 s[0:1], s[0:1], 1
	v_lshl_add_u64 v[100:101], v[130:131], 0, s[0:1]
	v_add_co_u32_e32 v88, vcc, s46, v100
	v_lshl_add_u64 v[120:121], v[132:133], 0, s[0:1]
	s_nop 0
	v_addc_co_u32_e32 v89, vcc, 0, v101, vcc
	v_add_co_u32_e32 v92, vcc, 0x20000, v100
	s_nop 1
	v_addc_co_u32_e32 v93, vcc, 0, v101, vcc
	v_add_co_u32_e32 v112, vcc, 0x30000, v100
	global_load_dwordx4 v[88:91], v[88:89], off offset:384
	s_nop 0
	global_load_dwordx4 v[92:95], v[92:93], off offset:384
	v_addc_co_u32_e32 v113, vcc, 0, v101, vcc
	v_add_co_u32_e32 v116, vcc, 0x10000, v120
	global_load_dwordx4 v[100:103], v[100:101], off offset:384
	s_nop 0
	global_load_dwordx4 v[108:111], v[120:121], off offset:384
	v_addc_co_u32_e32 v117, vcc, 0, v121, vcc
	v_add_co_u32_e32 v122, vcc, 0x20000, v120
	global_load_dwordx4 v[112:115], v[112:113], off offset:384
	s_nop 0
	global_load_dwordx4 v[116:119], v[116:117], off offset:384
	v_addc_co_u32_e32 v123, vcc, 0, v121, vcc
	v_add_co_u32_e32 v124, vcc, 0x30000, v120
	s_nop 1
	v_addc_co_u32_e32 v125, vcc, 0, v121, vcc
	global_load_dwordx4 v[120:123], v[122:123], off offset:384
	s_nop 0
	global_load_dwordx4 v[124:127], v[124:125], off offset:384
	s_branch .LBB0_1436
